# GEMM K-loops: the computing half arrives at the closing barrier 6 MFMAs early (MFMAs touch no memory), so the other half starts its MFMA block while the matrix pipe is still busy
# baseline (speedup 1.0000x reference)
; #define PG8_STAGE(bufoff, gbase, voff) do { _Pragma("unroll") for (int _i = 0; _i < 2; ++_i) \
;         __builtin_amdgcn_global_load_lds((const unsigned*)((const char*)(gbase) + (voff)[_i]), (PG8_LAS unsigned*)(lds + (bufoff) + ldsw + _i * 8192), 16, 0, 0); } while (0)
; #define PG8_LDA(dst, b, h) do { _Pragma("unroll") for (int m = 0; m < 4; ++m) _Pragma("unroll") for (int k = 0; k < 2; ++k) dst[m][k] = *(const PG8_LAS bf16x8*)(lds + PG8_SA(b, h) + aoff + m * 2048 + k * 1024); } while (0)
; #define PG8_LDB(dst, b, h) do { _Pragma("unroll") for (int n = 0; n < 2; ++n) _Pragma("unroll") for (int k = 0; k < 2; ++k) dst[n][k] = *(const PG8_LAS bf16x8*)(lds + PG8_SB(b, h) + boff + n * 2048 + k * 1024); } while (0)
; #define PG8_MMA(ai, bj, At, Bt) do { __builtin_amdgcn_s_setprio(1); _Pragma("unroll") for (int m = 0; m < 4; ++m) _Pragma("unroll") for (int n = 0; n < 2; ++n) _Pragma("unroll") for (int k = 0; k < 2; ++k) \
;         acc[ai][bj][m][n] = __builtin_amdgcn_mfma_f32_16x16x32_bf16(Bt[n][k], At[m][k], acc[ai][bj][m][n], 0, 0, 0); __builtin_amdgcn_s_setprio(0); } while (0)
; #define PG8_WAIT_V(n) asm volatile("s_waitcnt vmcnt(" #n ")" ::: "memory")
; #define PG8_WAIT_L(n) asm volatile("s_waitcnt lgkmcnt(" #n ")" ::: "memory")
; #define PG8_BAR __builtin_amdgcn_s_barrier()
; #define PG8_SCHED __builtin_amdgcn_sched_barrier(0)
; template <class Epi, class Sched, bool ALIGN_EPI = false, bool SP2 = false>
; __device__ __forceinline__ void gemm_phase(PG8_LAS unsigned char* lds, const Gemm g, const Sched& S, const Epi& E) {
;     ...
;             const bool last = (t == nt - 2);
;             const char* a1 = cA + (size_t)(t + 1) * kstep;
;             const char* a2 = last ? nA : cA + (size_t)(t + 2) * kstep; const char* b2 = last ? nB : cB + (size_t)(t + 2) * kstep;
;             const char* a3 = a2 + kstep; const char* b3 = b2 + kstep;
;             if (last && has_next) S.a_ready(nxt);
;             if constexpr (SP2) {
;             PG8_LDB(B0, 0, 0); PG8_LDB(B1, 0, 1); PG8_SCHED; PG8_LDA(At, 0, 0); PG8_STAGE(PG8_SA(1, 1), a1 + hstep, voffA);
;             PG8_WAIT_V(8); PG8_WAIT_L(0); PG8_BAR; PG8_MMA(0, 0, At, B0); PG8_MMA(0, 1, At, B1); PG8_BAR; PG8_SCHED;
;             PG8_LDA(At, 0, 1); PG8_STAGE(PG8_SB(0, 0), b2, voffB); PG8_STAGE(PG8_SB(0, 1), b2 + hstepB, voffB); PG8_STAGE(PG8_SA(0, 0), a2, voffA);
.LBB0_150:
	ds_read_b128 v[156:159], v150
	ds_read_b128 v[160:163], v150 offset:1024
	ds_read_b128 v[164:167], v150 offset:2048
	ds_read_b128 v[168:171], v150 offset:3072
	ds_read_b128 v[172:175], v151
	ds_read_b128 v[176:179], v151 offset:1024
	ds_read_b128 v[180:183], v151 offset:2048
	ds_read_b128 v[184:187], v151 offset:3072
	s_add_u32 s26, s24, 0x4000
	s_addc_u32 s27, s25, 0
	s_cmp_eq_u32 s75, 12
	s_cselect_b32 s40, s71, s26
	s_cselect_b32 s41, s17, s27
	s_cselect_b32 s28, s72, s73
	s_cselect_b32 s29, s15, s74
	s_add_u32 s26, s40, 0x8000
	s_addc_u32 s27, s41, 0
	v_lshl_add_u64 v[216:217], s[24:25], 0, v[140:141]
	s_add_i32 m0, s23, 0xc000
	ds_read_b128 v[188:191], v152
	ds_read_b128 v[192:195], v152 offset:1024
	ds_read_b128 v[196:199], v152 offset:2048
	ds_read_b128 v[200:203], v152 offset:3072
	ds_read_b128 v[204:207], v152 offset:4096
	ds_read_b128 v[208:211], v152 offset:5120
	ds_read_b128 v[212:215], v152 offset:6144
	ds_read_b128 v[220:223], v152 offset:7168
	global_load_lds_dwordx4 v[216:217], off
	v_lshl_add_u64 v[216:217], s[24:25], 0, v[142:143]
	s_add_i32 m0, s23, 0xe000
	s_nop 0
	global_load_lds_dwordx4 v[216:217], off
	s_waitcnt vmcnt(8)
	s_waitcnt lgkmcnt(0)
	s_setprio 1
	s_barrier
	v_mfma_f32_16x16x32_bf16 v[126:129], v[156:159], v[188:191], v[126:129]
	v_mfma_f32_16x16x32_bf16 v[122:125], v[164:167], v[188:191], v[122:125]
	v_mfma_f32_16x16x32_bf16 v[114:117], v[156:159], v[196:199], v[114:117]
	v_mfma_f32_16x16x32_bf16 v[106:109], v[164:167], v[196:199], v[106:109]
	v_mfma_f32_16x16x32_bf16 v[98:101], v[156:159], v[204:207], v[98:101]
	v_mfma_f32_16x16x32_bf16 v[90:93], v[164:167], v[204:207], v[90:93]
	v_mfma_f32_16x16x32_bf16 v[78:81], v[156:159], v[212:215], v[78:81]
	v_mfma_f32_16x16x32_bf16 v[74:77], v[164:167], v[212:215], v[74:77]
	v_mfma_f32_16x16x32_bf16 v[126:129], v[160:163], v[192:195], v[126:129]
	v_mfma_f32_16x16x32_bf16 v[122:125], v[168:171], v[192:195], v[122:125]
	v_mfma_f32_16x16x32_bf16 v[114:117], v[160:163], v[200:203], v[114:117]
	v_mfma_f32_16x16x32_bf16 v[106:109], v[168:171], v[200:203], v[106:109]
	v_mfma_f32_16x16x32_bf16 v[98:101], v[160:163], v[208:211], v[98:101]
	v_mfma_f32_16x16x32_bf16 v[90:93], v[168:171], v[208:211], v[90:93]
	v_mfma_f32_16x16x32_bf16 v[78:81], v[160:163], v[220:223], v[78:81]
	v_mfma_f32_16x16x32_bf16 v[74:77], v[168:171], v[220:223], v[74:77]
	s_setprio 0
	s_setprio 1
	v_mfma_f32_16x16x32_bf16 v[118:121], v[172:175], v[188:191], v[118:121]
	v_mfma_f32_16x16x32_bf16 v[110:113], v[180:183], v[188:191], v[110:113]
	v_mfma_f32_16x16x32_bf16 v[102:105], v[172:175], v[196:199], v[102:105]
	v_mfma_f32_16x16x32_bf16 v[94:97], v[180:183], v[196:199], v[94:97]
	v_mfma_f32_16x16x32_bf16 v[86:89], v[172:175], v[204:207], v[86:89]
	v_mfma_f32_16x16x32_bf16 v[82:85], v[180:183], v[204:207], v[82:85]
	v_mfma_f32_16x16x32_bf16 v[70:73], v[172:175], v[212:215], v[70:73]
	v_mfma_f32_16x16x32_bf16 v[66:69], v[180:183], v[212:215], v[66:69]
	v_mfma_f32_16x16x32_bf16 v[118:121], v[176:179], v[192:195], v[118:121]
	v_mfma_f32_16x16x32_bf16 v[110:113], v[184:187], v[192:195], v[110:113]
	s_barrier
	v_mfma_f32_16x16x32_bf16 v[102:105], v[176:179], v[200:203], v[102:105]
	v_mfma_f32_16x16x32_bf16 v[94:97], v[184:187], v[200:203], v[94:97]
	v_mfma_f32_16x16x32_bf16 v[86:89], v[176:179], v[208:211], v[86:89]
	v_mfma_f32_16x16x32_bf16 v[82:85], v[184:187], v[208:211], v[82:85]
	v_mfma_f32_16x16x32_bf16 v[70:73], v[176:179], v[220:223], v[70:73]
	v_mfma_f32_16x16x32_bf16 v[66:69], v[184:187], v[220:223], v[66:69]
	s_setprio 0
	s_add_i32 s76, s56, s0
	v_lshl_add_u64 v[216:217], s[28:29], 0, v[134:135]
	s_mov_b32 m0, s76
	ds_read_b128 v[188:191], v152 offset:16384
	ds_read_b128 v[192:195], v152 offset:17408
	ds_read_b128 v[196:199], v152 offset:18432
	ds_read_b128 v[200:203], v152 offset:19456
	ds_read_b128 v[204:207], v152 offset:20480
	ds_read_b128 v[208:211], v152 offset:21504
	ds_read_b128 v[212:215], v152 offset:22528
	ds_read_b128 v[220:223], v152 offset:23552
	global_load_lds_dwordx4 v[216:217], off
	s_add_i32 m0, s76, 0x2000
	s_add_u32 s76, s28, 0x1000
	v_lshl_add_u64 v[216:217], s[28:29], 0, v[130:131]
	s_addc_u32 s77, s29, 0
	s_add_i32 s78, s57, s0
	global_load_lds_dwordx4 v[216:217], off
	v_lshl_add_u64 v[216:217], s[76:77], 0, v[134:135]
	s_mov_b32 m0, s78
	s_nop 0
	global_load_lds_dwordx4 v[216:217], off
	v_lshl_add_u64 v[216:217], s[76:77], 0, v[130:131]
	s_add_i32 m0, s78, 0x2000
	s_nop 0
	global_load_lds_dwordx4 v[216:217], off
	v_lshl_add_u64 v[216:217], s[40:41], 0, v[136:137]
	s_mov_b32 m0, s23
	s_nop 0
	global_load_lds_dwordx4 v[216:217], off
	v_lshl_add_u64 v[216:217], s[40:41], 0, v[132:133]
	s_mov_b32 m0, s49
	s_nop 0
	global_load_lds_dwordx4 v[216:217], off
	s_waitcnt vmcnt(8)
	s_waitcnt lgkmcnt(0)
	s_setprio 1
	s_barrier
; #define PG8_STAGE(bufoff, gbase, voff) do { _Pragma("unroll") for (int _i = 0; _i < 2; ++_i) \
;         __builtin_amdgcn_global_load_lds((const unsigned*)((const char*)(gbase) + (voff)[_i]), (PG8_LAS unsigned*)(lds + (bufoff) + ldsw + _i * 8192), 16, 0, 0); } while (0)
; #define PG8_LDA(dst, b, h) do { _Pragma("unroll") for (int m = 0; m < 4; ++m) _Pragma("unroll") for (int k = 0; k < 2; ++k) dst[m][k] = *(const PG8_LAS bf16x8*)(lds + PG8_SA(b, h) + aoff + m * 2048 + k * 1024); } while (0)
; #define PG8_LDB(dst, b, h) do { _Pragma("unroll") for (int n = 0; n < 2; ++n) _Pragma("unroll") for (int k = 0; k < 2; ++k) dst[n][k] = *(const PG8_LAS bf16x8*)(lds + PG8_SB(b, h) + boff + n * 2048 + k * 1024); } while (0)
; #define PG8_MMA(ai, bj, At, Bt) do { __builtin_amdgcn_s_setprio(1); _Pragma("unroll") for (int m = 0; m < 4; ++m) _Pragma("unroll") for (int n = 0; n < 2; ++n) _Pragma("unroll") for (int k = 0; k < 2; ++k) \
;         acc[ai][bj][m][n] = __builtin_amdgcn_mfma_f32_16x16x32_bf16(Bt[n][k], At[m][k], acc[ai][bj][m][n], 0, 0, 0); __builtin_amdgcn_s_setprio(0); } while (0)
; #define PG8_WAIT_V(n) asm volatile("s_waitcnt vmcnt(" #n ")" ::: "memory")
; #define PG8_WAIT_L(n) asm volatile("s_waitcnt lgkmcnt(" #n ")" ::: "memory")
; #define PG8_BAR __builtin_amdgcn_s_barrier()
; #define PG8_SCHED __builtin_amdgcn_sched_barrier(0)
; template <class Epi, class Sched, bool ALIGN_EPI = false, bool SP2 = false>
; __device__ __forceinline__ void gemm_phase(PG8_LAS unsigned char* lds, const Gemm g, const Sched& S, const Epi& E) {
;     ...
;             PG8_LDA(At, 0, 1); PG8_STAGE(PG8_SB(0, 0), b2, voffB); PG8_STAGE(PG8_SB(0, 1), b2 + hstepB, voffB); PG8_STAGE(PG8_SA(0, 0), a2, voffA);
;             PG8_WAIT_V(8); PG8_WAIT_L(0); PG8_BAR; PG8_MMA(1, 0, At, B0); PG8_MMA(1, 1, At, B1); PG8_BAR; PG8_SCHED;
;             PG8_LDB(B0, 1, 0); PG8_LDB(B1, 1, 1); PG8_SCHED; PG8_LDA(At, 1, 0); PG8_STAGE(PG8_SA(0, 1), a2 + hstep, voffA);
;             PG8_WAIT_V(8); PG8_WAIT_L(0); PG8_BAR; PG8_MMA(0, 0, At, B0); PG8_MMA(0, 1, At, B1); PG8_BAR; PG8_SCHED;
	v_mfma_f32_16x16x32_bf16 v[62:65], v[156:159], v[188:191], v[62:65]
	v_mfma_f32_16x16x32_bf16 v[58:61], v[164:167], v[188:191], v[58:61]
	v_mfma_f32_16x16x32_bf16 v[46:49], v[156:159], v[196:199], v[46:49]
	v_mfma_f32_16x16x32_bf16 v[42:45], v[164:167], v[196:199], v[42:45]
	v_mfma_f32_16x16x32_bf16 v[34:37], v[156:159], v[204:207], v[34:37]
	v_mfma_f32_16x16x32_bf16 v[26:29], v[164:167], v[204:207], v[26:29]
	v_mfma_f32_16x16x32_bf16 v[18:21], v[156:159], v[212:215], v[18:21]
	v_mfma_f32_16x16x32_bf16 v[10:13], v[164:167], v[212:215], v[10:13]
	v_mfma_f32_16x16x32_bf16 v[62:65], v[160:163], v[192:195], v[62:65]
	v_mfma_f32_16x16x32_bf16 v[58:61], v[168:171], v[192:195], v[58:61]
	v_mfma_f32_16x16x32_bf16 v[46:49], v[160:163], v[200:203], v[46:49]
	v_mfma_f32_16x16x32_bf16 v[42:45], v[168:171], v[200:203], v[42:45]
	v_mfma_f32_16x16x32_bf16 v[34:37], v[160:163], v[208:211], v[34:37]
	v_mfma_f32_16x16x32_bf16 v[26:29], v[168:171], v[208:211], v[26:29]
	v_mfma_f32_16x16x32_bf16 v[18:21], v[160:163], v[220:223], v[18:21]
	v_mfma_f32_16x16x32_bf16 v[10:13], v[168:171], v[220:223], v[10:13]
	s_setprio 0
	s_setprio 1
	v_mfma_f32_16x16x32_bf16 v[54:57], v[172:175], v[188:191], v[54:57]
	v_mfma_f32_16x16x32_bf16 v[50:53], v[180:183], v[188:191], v[50:53]
	v_mfma_f32_16x16x32_bf16 v[38:41], v[172:175], v[196:199], v[38:41]
	v_mfma_f32_16x16x32_bf16 v[30:33], v[180:183], v[196:199], v[30:33]
	v_mfma_f32_16x16x32_bf16 v[22:25], v[172:175], v[204:207], v[22:25]
	v_mfma_f32_16x16x32_bf16 v[14:17], v[180:183], v[204:207], v[14:17]
	v_mfma_f32_16x16x32_bf16 v[6:9], v[172:175], v[212:215], v[6:9]
	v_mfma_f32_16x16x32_bf16 v[2:5], v[180:183], v[212:215], v[2:5]
	v_mfma_f32_16x16x32_bf16 v[54:57], v[176:179], v[192:195], v[54:57]
	v_mfma_f32_16x16x32_bf16 v[50:53], v[184:187], v[192:195], v[50:53]
	s_barrier
	v_mfma_f32_16x16x32_bf16 v[38:41], v[176:179], v[200:203], v[38:41]
	v_mfma_f32_16x16x32_bf16 v[30:33], v[184:187], v[200:203], v[30:33]
	v_mfma_f32_16x16x32_bf16 v[22:25], v[176:179], v[208:211], v[22:25]
	v_mfma_f32_16x16x32_bf16 v[14:17], v[184:187], v[208:211], v[14:17]
	v_mfma_f32_16x16x32_bf16 v[6:9], v[176:179], v[220:223], v[6:9]
	v_mfma_f32_16x16x32_bf16 v[2:5], v[184:187], v[220:223], v[2:5]
	s_setprio 0
	s_add_i32 s76, 0, 0x18000
	v_add_u32_e32 v148, s76, v149
	s_add_i32 s77, 0, 0x1c000
	ds_read_b128 v[156:159], v148
	ds_read_b128 v[160:163], v148 offset:1024
	ds_read_b128 v[164:167], v148 offset:2048
	ds_read_b128 v[168:171], v148 offset:3072
	v_add_u32_e32 v148, s77, v149
	ds_read_b128 v[172:175], v148
	ds_read_b128 v[176:179], v148 offset:1024
	ds_read_b128 v[180:183], v148 offset:2048
	ds_read_b128 v[184:187], v148 offset:3072
	s_add_u32 s40, s40, 0x4000
	s_addc_u32 s41, s41, 0
	s_mov_b32 m0, s50
	v_lshl_add_u64 v[216:217], s[40:41], 0, v[136:137]
	ds_read_b128 v[188:191], v152 offset:32768
	ds_read_b128 v[192:195], v152 offset:33792
	ds_read_b128 v[196:199], v152 offset:34816
	ds_read_b128 v[200:203], v152 offset:35840
	ds_read_b128 v[204:207], v152 offset:36864
	ds_read_b128 v[208:211], v152 offset:37888
	ds_read_b128 v[212:215], v152 offset:38912
	ds_read_b128 v[220:223], v152 offset:39936
	global_load_lds_dwordx4 v[216:217], off
	v_lshl_add_u64 v[216:217], s[40:41], 0, v[132:133]
	s_mov_b32 m0, s51
	s_nop 0
	global_load_lds_dwordx4 v[216:217], off
	s_waitcnt vmcnt(8)
	s_waitcnt lgkmcnt(0)
	s_setprio 1
	s_barrier
	v_mfma_f32_16x16x32_bf16 v[126:129], v[156:159], v[188:191], v[126:129]
	v_mfma_f32_16x16x32_bf16 v[122:125], v[164:167], v[188:191], v[122:125]
	v_mfma_f32_16x16x32_bf16 v[114:117], v[156:159], v[196:199], v[114:117]
	v_mfma_f32_16x16x32_bf16 v[106:109], v[164:167], v[196:199], v[106:109]
	v_mfma_f32_16x16x32_bf16 v[98:101], v[156:159], v[204:207], v[98:101]
	v_mfma_f32_16x16x32_bf16 v[90:93], v[164:167], v[204:207], v[90:93]
	v_mfma_f32_16x16x32_bf16 v[78:81], v[156:159], v[212:215], v[78:81]
	v_mfma_f32_16x16x32_bf16 v[74:77], v[164:167], v[212:215], v[74:77]
	v_mfma_f32_16x16x32_bf16 v[126:129], v[160:163], v[192:195], v[126:129]
	v_mfma_f32_16x16x32_bf16 v[122:125], v[168:171], v[192:195], v[122:125]
	v_mfma_f32_16x16x32_bf16 v[114:117], v[160:163], v[200:203], v[114:117]
	v_mfma_f32_16x16x32_bf16 v[106:109], v[168:171], v[200:203], v[106:109]
	v_mfma_f32_16x16x32_bf16 v[98:101], v[160:163], v[208:211], v[98:101]
	v_mfma_f32_16x16x32_bf16 v[90:93], v[168:171], v[208:211], v[90:93]
	v_mfma_f32_16x16x32_bf16 v[78:81], v[160:163], v[220:223], v[78:81]
	v_mfma_f32_16x16x32_bf16 v[74:77], v[168:171], v[220:223], v[74:77]
	s_setprio 0
	s_setprio 1
	v_mfma_f32_16x16x32_bf16 v[118:121], v[172:175], v[188:191], v[118:121]
	v_mfma_f32_16x16x32_bf16 v[110:113], v[180:183], v[188:191], v[110:113]
	v_mfma_f32_16x16x32_bf16 v[102:105], v[172:175], v[196:199], v[102:105]
	v_mfma_f32_16x16x32_bf16 v[94:97], v[180:183], v[196:199], v[94:97]
	v_mfma_f32_16x16x32_bf16 v[86:89], v[172:175], v[204:207], v[86:89]
	v_mfma_f32_16x16x32_bf16 v[82:85], v[180:183], v[204:207], v[82:85]
	v_mfma_f32_16x16x32_bf16 v[70:73], v[172:175], v[212:215], v[70:73]
	v_mfma_f32_16x16x32_bf16 v[66:69], v[180:183], v[212:215], v[66:69]
	v_mfma_f32_16x16x32_bf16 v[118:121], v[176:179], v[192:195], v[118:121]
	v_mfma_f32_16x16x32_bf16 v[110:113], v[184:187], v[192:195], v[110:113]
	s_barrier
; #define PG8_STAGE(bufoff, gbase, voff) do { _Pragma("unroll") for (int _i = 0; _i < 2; ++_i) \
;         __builtin_amdgcn_global_load_lds((const unsigned*)((const char*)(gbase) + (voff)[_i]), (PG8_LAS unsigned*)(lds + (bufoff) + ldsw + _i * 8192), 16, 0, 0); } while (0)
; #define PG8_LDA(dst, b, h) do { _Pragma("unroll") for (int m = 0; m < 4; ++m) _Pragma("unroll") for (int k = 0; k < 2; ++k) dst[m][k] = *(const PG8_LAS bf16x8*)(lds + PG8_SA(b, h) + aoff + m * 2048 + k * 1024); } while (0)
; #define PG8_MMA(ai, bj, At, Bt) do { __builtin_amdgcn_s_setprio(1); _Pragma("unroll") for (int m = 0; m < 4; ++m) _Pragma("unroll") for (int n = 0; n < 2; ++n) _Pragma("unroll") for (int k = 0; k < 2; ++k) \
;         acc[ai][bj][m][n] = __builtin_amdgcn_mfma_f32_16x16x32_bf16(Bt[n][k], At[m][k], acc[ai][bj][m][n], 0, 0, 0); __builtin_amdgcn_s_setprio(0); } while (0)
; #define PG8_WAIT_V(n) asm volatile("s_waitcnt vmcnt(" #n ")" ::: "memory")
; #define PG8_WAIT_L(n) asm volatile("s_waitcnt lgkmcnt(" #n ")" ::: "memory")
; #define PG8_BAR __builtin_amdgcn_s_barrier()
; #define PG8_SCHED __builtin_amdgcn_sched_barrier(0)
; template <class Epi, class Sched, bool ALIGN_EPI = false, bool SP2 = false>
; __device__ __forceinline__ void gemm_phase(PG8_LAS unsigned char* lds, const Gemm g, const Sched& S, const Epi& E) {
;     ...
;             PG8_WAIT_V(8); PG8_WAIT_L(0); PG8_BAR; PG8_MMA(0, 0, At, B0); PG8_MMA(0, 1, At, B1); PG8_BAR; PG8_SCHED;
;             PG8_LDA(At, 1, 1); PG8_STAGE(PG8_SB(1, 0), b3, voffB); PG8_STAGE(PG8_SB(1, 1), b3 + hstepB, voffB); PG8_STAGE(PG8_SA(1, 0), a3, voffA);
;             PG8_WAIT_V(8); PG8_WAIT_L(0); PG8_BAR; PG8_MMA(1, 0, At, B0); PG8_MMA(1, 1, At, B1); PG8_BAR; PG8_SCHED;
;     ...
;         if constexpr (ALIGN_EPI) { if (wr == 0) PG8_BAR; }
	v_mfma_f32_16x16x32_bf16 v[102:105], v[176:179], v[200:203], v[102:105]
	v_mfma_f32_16x16x32_bf16 v[94:97], v[184:187], v[200:203], v[94:97]
	v_mfma_f32_16x16x32_bf16 v[86:89], v[176:179], v[208:211], v[86:89]
	v_mfma_f32_16x16x32_bf16 v[82:85], v[184:187], v[208:211], v[82:85]
	v_mfma_f32_16x16x32_bf16 v[70:73], v[176:179], v[220:223], v[70:73]
	v_mfma_f32_16x16x32_bf16 v[66:69], v[184:187], v[220:223], v[66:69]
	s_setprio 0
	s_add_u32 s40, s28, 0x8000
	s_addc_u32 s41, s29, 0
	s_add_i32 s76, s76, s0
	v_lshl_add_u64 v[216:217], s[40:41], 0, v[134:135]
	s_mov_b32 m0, s76
	ds_read_b128 v[188:191], v152 offset:49152
	ds_read_b128 v[192:195], v152 offset:50176
	ds_read_b128 v[196:199], v152 offset:51200
	ds_read_b128 v[200:203], v152 offset:52224
	ds_read_b128 v[204:207], v152 offset:53248
	ds_read_b128 v[208:211], v152 offset:54272
	ds_read_b128 v[212:215], v152 offset:55296
	ds_read_b128 v[220:223], v152 offset:56320
	global_load_lds_dwordx4 v[216:217], off
	s_add_i32 m0, s76, 0x2000
	s_add_u32 s28, s28, 0x9000
	v_lshl_add_u64 v[216:217], s[40:41], 0, v[130:131]
	s_addc_u32 s29, s29, 0
	s_add_i32 s40, s77, s0
	global_load_lds_dwordx4 v[216:217], off
	v_lshl_add_u64 v[216:217], s[28:29], 0, v[134:135]
	s_mov_b32 m0, s40
	s_nop 0
	global_load_lds_dwordx4 v[216:217], off
	v_lshl_add_u64 v[216:217], s[28:29], 0, v[130:131]
	s_add_i32 m0, s40, 0x2000
	s_nop 0
	global_load_lds_dwordx4 v[216:217], off
	v_lshl_add_u64 v[216:217], s[26:27], 0, v[136:137]
	s_mov_b32 m0, s54
	s_nop 0
	global_load_lds_dwordx4 v[216:217], off
	v_lshl_add_u64 v[216:217], s[26:27], 0, v[132:133]
	s_mov_b32 m0, s55
	s_nop 0
	global_load_lds_dwordx4 v[216:217], off
	s_waitcnt vmcnt(8)
	s_waitcnt lgkmcnt(0)
	s_setprio 1
	s_barrier
	v_mfma_f32_16x16x32_bf16 v[62:65], v[156:159], v[188:191], v[62:65]
	v_mfma_f32_16x16x32_bf16 v[58:61], v[164:167], v[188:191], v[58:61]
	v_mfma_f32_16x16x32_bf16 v[46:49], v[156:159], v[196:199], v[46:49]
	v_mfma_f32_16x16x32_bf16 v[42:45], v[164:167], v[196:199], v[42:45]
	v_mfma_f32_16x16x32_bf16 v[34:37], v[156:159], v[204:207], v[34:37]
	v_mfma_f32_16x16x32_bf16 v[26:29], v[164:167], v[204:207], v[26:29]
	v_mfma_f32_16x16x32_bf16 v[18:21], v[156:159], v[212:215], v[18:21]
	v_mfma_f32_16x16x32_bf16 v[10:13], v[164:167], v[212:215], v[10:13]
	v_mfma_f32_16x16x32_bf16 v[62:65], v[160:163], v[192:195], v[62:65]
	v_mfma_f32_16x16x32_bf16 v[58:61], v[168:171], v[192:195], v[58:61]
	v_mfma_f32_16x16x32_bf16 v[46:49], v[160:163], v[200:203], v[46:49]
	v_mfma_f32_16x16x32_bf16 v[42:45], v[168:171], v[200:203], v[42:45]
	v_mfma_f32_16x16x32_bf16 v[34:37], v[160:163], v[208:211], v[34:37]
	v_mfma_f32_16x16x32_bf16 v[26:29], v[168:171], v[208:211], v[26:29]
	v_mfma_f32_16x16x32_bf16 v[18:21], v[160:163], v[220:223], v[18:21]
	v_mfma_f32_16x16x32_bf16 v[10:13], v[168:171], v[220:223], v[10:13]
	s_setprio 0
	s_setprio 1
	v_mfma_f32_16x16x32_bf16 v[54:57], v[172:175], v[188:191], v[54:57]
	v_mfma_f32_16x16x32_bf16 v[50:53], v[180:183], v[188:191], v[50:53]
	v_mfma_f32_16x16x32_bf16 v[38:41], v[172:175], v[196:199], v[38:41]
	v_mfma_f32_16x16x32_bf16 v[30:33], v[180:183], v[196:199], v[30:33]
	v_mfma_f32_16x16x32_bf16 v[22:25], v[172:175], v[204:207], v[22:25]
	v_mfma_f32_16x16x32_bf16 v[14:17], v[180:183], v[204:207], v[14:17]
	v_mfma_f32_16x16x32_bf16 v[6:9], v[172:175], v[212:215], v[6:9]
	v_mfma_f32_16x16x32_bf16 v[2:5], v[180:183], v[212:215], v[2:5]
	v_mfma_f32_16x16x32_bf16 v[54:57], v[176:179], v[192:195], v[54:57]
	v_mfma_f32_16x16x32_bf16 v[50:53], v[184:187], v[192:195], v[50:53]
	s_barrier
	v_mfma_f32_16x16x32_bf16 v[38:41], v[176:179], v[200:203], v[38:41]
	v_mfma_f32_16x16x32_bf16 v[30:33], v[184:187], v[200:203], v[30:33]
	v_mfma_f32_16x16x32_bf16 v[22:25], v[176:179], v[208:211], v[22:25]
	v_mfma_f32_16x16x32_bf16 v[14:17], v[184:187], v[208:211], v[14:17]
	v_mfma_f32_16x16x32_bf16 v[6:9], v[176:179], v[220:223], v[6:9]
	v_mfma_f32_16x16x32_bf16 v[2:5], v[184:187], v[220:223], v[2:5]
	s_setprio 0
	s_add_i32 s75, s75, 2
	s_add_u32 s24, s24, 0x10000
	s_addc_u32 s25, s25, 0
	s_add_u32 s73, s73, 0x10000
	s_addc_u32 s74, s74, 0
	s_cmp_gt_u32 s75, 13
	s_cbranch_scc0 .LBB0_150
	s_and_b64 vcc, exec, s[12:13]
	s_cbranch_vccz .LBB0_153
	s_barrier

; #define PG8_STAGE(bufoff, gbase, voff) do { _Pragma("unroll") for (int _i = 0; _i < 2; ++_i) \
;         __builtin_amdgcn_global_load_lds((const unsigned*)((const char*)(gbase) + (voff)[_i]), (PG8_LAS unsigned*)(lds + (bufoff) + ldsw + _i * 8192), 16, 0, 0); } while (0)
; #define PG8_LDA(dst, b, h) do { _Pragma("unroll") for (int m = 0; m < 4; ++m) _Pragma("unroll") for (int k = 0; k < 2; ++k) dst[m][k] = *(const PG8_LAS bf16x8*)(lds + PG8_SA(b, h) + aoff + m * 2048 + k * 1024); } while (0)
; #define PG8_LDB(dst, b, h) do { _Pragma("unroll") for (int n = 0; n < 2; ++n) _Pragma("unroll") for (int k = 0; k < 2; ++k) dst[n][k] = *(const PG8_LAS bf16x8*)(lds + PG8_SB(b, h) + boff + n * 2048 + k * 1024); } while (0)
; #define PG8_MMA(ai, bj, At, Bt) do { __builtin_amdgcn_s_setprio(1); _Pragma("unroll") for (int m = 0; m < 4; ++m) _Pragma("unroll") for (int n = 0; n < 2; ++n) _Pragma("unroll") for (int k = 0; k < 2; ++k) \
;         acc[ai][bj][m][n] = __builtin_amdgcn_mfma_f32_16x16x32_bf16(Bt[n][k], At[m][k], acc[ai][bj][m][n], 0, 0, 0); __builtin_amdgcn_s_setprio(0); } while (0)
; #define PG8_WAIT_V(n) asm volatile("s_waitcnt vmcnt(" #n ")" ::: "memory")
; #define PG8_WAIT_L(n) asm volatile("s_waitcnt lgkmcnt(" #n ")" ::: "memory")
; #define PG8_BAR __builtin_amdgcn_s_barrier()
; #define PG8_SCHED __builtin_amdgcn_sched_barrier(0)
; template <class Epi, class Sched, bool ALIGN_EPI = false, bool SP2 = false>
; __device__ __forceinline__ void gemm_phase(PG8_LAS unsigned char* lds, const Gemm g, const Sched& S, const Epi& E) {
;     ...
;             const bool last = (t == nt - 2);
;             const char* a1 = cA + (size_t)(t + 1) * kstep;
;             const char* a2 = last ? nA : cA + (size_t)(t + 2) * kstep; const char* b2 = last ? nB : cB + (size_t)(t + 2) * kstep;
;             const char* a3 = a2 + kstep; const char* b3 = b2 + kstep;
;             if (last && has_next) S.a_ready(nxt);
;             if constexpr (SP2) {
;             PG8_LDB(B0, 0, 0); PG8_LDB(B1, 0, 1); PG8_SCHED; PG8_LDA(At, 0, 0); PG8_STAGE(PG8_SA(1, 1), a1 + hstep, voffA);
;             PG8_WAIT_V(8); PG8_WAIT_L(0); PG8_BAR; PG8_MMA(0, 0, At, B0); PG8_MMA(0, 1, At, B1); PG8_BAR; PG8_SCHED;
;             PG8_LDA(At, 0, 1); PG8_STAGE(PG8_SB(0, 0), b2, voffB); PG8_STAGE(PG8_SB(0, 1), b2 + hstepB, voffB); PG8_STAGE(PG8_SA(0, 0), a2, voffA);
.LBB0_380:
	s_add_u32 s48, s28, s46
	v_add_u32_e32 v3, s87, v221
	s_addc_u32 s49, s29, s47
	ds_read_b128 v[134:137], v3
	ds_read_b128 v[138:141], v3 offset:1024
	ds_read_b128 v[142:145], v3 offset:2048
	ds_read_b128 v[146:149], v3 offset:3072
	v_add_u32_e32 v3, s88, v221
	s_add_u32 s48, s48, 0x10000
	ds_read_b128 v[150:153], v3
	ds_read_b128 v[154:157], v3 offset:1024
	ds_read_b128 v[158:161], v3 offset:2048
	ds_read_b128 v[162:165], v3 offset:3072
	s_addc_u32 s49, s49, 0
	s_add_u32 s50, s27, s46
	s_addc_u32 s51, s45, s47
	s_cmp_eq_u32 s46, 0x70000
	s_cselect_b32 s70, s1, s48
	s_cselect_b32 s71, s0, s49
	s_cselect_b32 s50, s21, s50
	s_cselect_b32 s51, s19, s51
	s_add_u32 s48, s70, 0x8000
	s_addc_u32 s49, s71, 0
	v_lshl_add_u64 v[4:5], v[182:183], 0, s[46:47]
	s_add_i32 m0, s74, 0xc000
	ds_read_b128 v[166:169], v225
	ds_read_b128 v[170:173], v225 offset:1024
	ds_read_b128 v[174:177], v225 offset:2048
	ds_read_b128 v[178:181], v225 offset:3072
	ds_read_b128 v[186:189], v225 offset:4096
	ds_read_b128 v[190:193], v225 offset:5120
	ds_read_b128 v[194:197], v225 offset:6144
	ds_read_b128 v[228:231], v225 offset:7168
	global_load_lds_dwordx4 v[4:5], off
	v_lshl_add_u64 v[4:5], v[184:185], 0, s[46:47]
	s_add_i32 m0, s74, 0xe000
	s_nop 0
	global_load_lds_dwordx4 v[4:5], off
	s_waitcnt vmcnt(8)
	s_waitcnt lgkmcnt(0)
	s_setprio 1
	s_barrier
	v_mfma_f32_16x16x32_bf16 v[130:133], v[134:137], v[166:169], v[130:133]
	v_mfma_f32_16x16x32_bf16 v[126:129], v[142:145], v[166:169], v[126:129]
	v_mfma_f32_16x16x32_bf16 v[114:117], v[134:137], v[174:177], v[114:117]
	v_mfma_f32_16x16x32_bf16 v[110:113], v[142:145], v[174:177], v[110:113]
	v_mfma_f32_16x16x32_bf16 v[98:101], v[134:137], v[186:189], v[98:101]
	v_mfma_f32_16x16x32_bf16 v[94:97], v[142:145], v[186:189], v[94:97]
	v_mfma_f32_16x16x32_bf16 v[82:85], v[134:137], v[194:197], v[82:85]
	v_mfma_f32_16x16x32_bf16 v[78:81], v[142:145], v[194:197], v[78:81]
	v_mfma_f32_16x16x32_bf16 v[130:133], v[138:141], v[170:173], v[130:133]
	v_mfma_f32_16x16x32_bf16 v[126:129], v[146:149], v[170:173], v[126:129]
	v_mfma_f32_16x16x32_bf16 v[114:117], v[138:141], v[178:181], v[114:117]
	v_mfma_f32_16x16x32_bf16 v[110:113], v[146:149], v[178:181], v[110:113]
	v_mfma_f32_16x16x32_bf16 v[98:101], v[138:141], v[190:193], v[98:101]
	v_mfma_f32_16x16x32_bf16 v[94:97], v[146:149], v[190:193], v[94:97]
	v_mfma_f32_16x16x32_bf16 v[82:85], v[138:141], v[228:231], v[82:85]
	v_mfma_f32_16x16x32_bf16 v[78:81], v[146:149], v[228:231], v[78:81]
	s_setprio 0
	s_setprio 1
	v_mfma_f32_16x16x32_bf16 v[122:125], v[150:153], v[166:169], v[122:125]
	v_mfma_f32_16x16x32_bf16 v[118:121], v[158:161], v[166:169], v[118:121]
	v_mfma_f32_16x16x32_bf16 v[106:109], v[150:153], v[174:177], v[106:109]
	v_mfma_f32_16x16x32_bf16 v[102:105], v[158:161], v[174:177], v[102:105]
	v_mfma_f32_16x16x32_bf16 v[90:93], v[150:153], v[186:189], v[90:93]
	v_mfma_f32_16x16x32_bf16 v[86:89], v[158:161], v[186:189], v[86:89]
	v_mfma_f32_16x16x32_bf16 v[74:77], v[150:153], v[194:197], v[74:77]
	v_mfma_f32_16x16x32_bf16 v[70:73], v[158:161], v[194:197], v[70:73]
	v_mfma_f32_16x16x32_bf16 v[122:125], v[154:157], v[170:173], v[122:125]
	v_mfma_f32_16x16x32_bf16 v[118:121], v[162:165], v[170:173], v[118:121]
	s_barrier
	v_mfma_f32_16x16x32_bf16 v[106:109], v[154:157], v[178:181], v[106:109]
	v_mfma_f32_16x16x32_bf16 v[102:105], v[162:165], v[178:181], v[102:105]
	v_mfma_f32_16x16x32_bf16 v[90:93], v[154:157], v[190:193], v[90:93]
	v_mfma_f32_16x16x32_bf16 v[86:89], v[162:165], v[190:193], v[86:89]
	v_mfma_f32_16x16x32_bf16 v[74:77], v[154:157], v[228:231], v[74:77]
	v_mfma_f32_16x16x32_bf16 v[70:73], v[162:165], v[228:231], v[70:73]
	s_setprio 0
	s_add_i32 s52, s87, s73
	v_lshl_add_u64 v[4:5], s[50:51], 0, v[200:201]
	s_mov_b32 m0, s52
	ds_read_b128 v[166:169], v225 offset:16384
	ds_read_b128 v[170:173], v225 offset:17408
	ds_read_b128 v[174:177], v225 offset:18432
	ds_read_b128 v[178:181], v225 offset:19456
	ds_read_b128 v[186:189], v225 offset:20480
	ds_read_b128 v[190:193], v225 offset:21504
	ds_read_b128 v[194:197], v225 offset:22528
	ds_read_b128 v[228:231], v225 offset:23552
	global_load_lds_dwordx4 v[4:5], off
	s_add_i32 m0, s52, 0x2000
	s_add_u32 s52, s50, 0x1000
	v_lshl_add_u64 v[4:5], s[50:51], 0, v[204:205]
	s_addc_u32 s53, s51, 0
	s_add_i32 s54, s88, s73
	global_load_lds_dwordx4 v[4:5], off
	v_lshl_add_u64 v[4:5], s[52:53], 0, v[200:201]
	s_mov_b32 m0, s54
	s_nop 0
	global_load_lds_dwordx4 v[4:5], off
	v_lshl_add_u64 v[4:5], s[52:53], 0, v[204:205]
	s_add_i32 m0, s54, 0x2000
	s_nop 0
	global_load_lds_dwordx4 v[4:5], off
	v_lshl_add_u64 v[4:5], s[70:71], 0, v[198:199]
	s_mov_b32 m0, s74
	s_nop 0
	global_load_lds_dwordx4 v[4:5], off
	v_lshl_add_u64 v[4:5], s[70:71], 0, v[202:203]
	s_mov_b32 m0, s75
	s_nop 0
	global_load_lds_dwordx4 v[4:5], off
	s_waitcnt vmcnt(8)
	s_waitcnt lgkmcnt(0)
	s_setprio 1
	s_barrier
; #define PG8_STAGE(bufoff, gbase, voff) do { _Pragma("unroll") for (int _i = 0; _i < 2; ++_i) \
;         __builtin_amdgcn_global_load_lds((const unsigned*)((const char*)(gbase) + (voff)[_i]), (PG8_LAS unsigned*)(lds + (bufoff) + ldsw + _i * 8192), 16, 0, 0); } while (0)
; #define PG8_LDA(dst, b, h) do { _Pragma("unroll") for (int m = 0; m < 4; ++m) _Pragma("unroll") for (int k = 0; k < 2; ++k) dst[m][k] = *(const PG8_LAS bf16x8*)(lds + PG8_SA(b, h) + aoff + m * 2048 + k * 1024); } while (0)
; #define PG8_LDB(dst, b, h) do { _Pragma("unroll") for (int n = 0; n < 2; ++n) _Pragma("unroll") for (int k = 0; k < 2; ++k) dst[n][k] = *(const PG8_LAS bf16x8*)(lds + PG8_SB(b, h) + boff + n * 2048 + k * 1024); } while (0)
; #define PG8_MMA(ai, bj, At, Bt) do { __builtin_amdgcn_s_setprio(1); _Pragma("unroll") for (int m = 0; m < 4; ++m) _Pragma("unroll") for (int n = 0; n < 2; ++n) _Pragma("unroll") for (int k = 0; k < 2; ++k) \
;         acc[ai][bj][m][n] = __builtin_amdgcn_mfma_f32_16x16x32_bf16(Bt[n][k], At[m][k], acc[ai][bj][m][n], 0, 0, 0); __builtin_amdgcn_s_setprio(0); } while (0)
; #define PG8_WAIT_V(n) asm volatile("s_waitcnt vmcnt(" #n ")" ::: "memory")
; #define PG8_WAIT_L(n) asm volatile("s_waitcnt lgkmcnt(" #n ")" ::: "memory")
; #define PG8_BAR __builtin_amdgcn_s_barrier()
; #define PG8_SCHED __builtin_amdgcn_sched_barrier(0)
; template <class Epi, class Sched, bool ALIGN_EPI = false, bool SP2 = false>
; __device__ __forceinline__ void gemm_phase(PG8_LAS unsigned char* lds, const Gemm g, const Sched& S, const Epi& E) {
;     ...
;             PG8_LDA(At, 0, 1); PG8_STAGE(PG8_SB(0, 0), b2, voffB); PG8_STAGE(PG8_SB(0, 1), b2 + hstepB, voffB); PG8_STAGE(PG8_SA(0, 0), a2, voffA);
;             PG8_WAIT_V(8); PG8_WAIT_L(0); PG8_BAR; PG8_MMA(1, 0, At, B0); PG8_MMA(1, 1, At, B1); PG8_BAR; PG8_SCHED;
;             PG8_LDB(B0, 1, 0); PG8_LDB(B1, 1, 1); PG8_SCHED; PG8_LDA(At, 1, 0); PG8_STAGE(PG8_SA(0, 1), a2 + hstep, voffA);
;             PG8_WAIT_V(8); PG8_WAIT_L(0); PG8_BAR; PG8_MMA(0, 0, At, B0); PG8_MMA(0, 1, At, B1); PG8_BAR; PG8_SCHED;
	v_mfma_f32_16x16x32_bf16 v[66:69], v[134:137], v[166:169], v[66:69]
	v_mfma_f32_16x16x32_bf16 v[62:65], v[142:145], v[166:169], v[62:65]
	v_mfma_f32_16x16x32_bf16 v[50:53], v[134:137], v[174:177], v[50:53]
	v_mfma_f32_16x16x32_bf16 v[46:49], v[142:145], v[174:177], v[46:49]
	v_mfma_f32_16x16x32_bf16 v[34:37], v[134:137], v[186:189], v[34:37]
	v_mfma_f32_16x16x32_bf16 v[30:33], v[142:145], v[186:189], v[30:33]
	v_mfma_f32_16x16x32_bf16 v[18:21], v[134:137], v[194:197], v[18:21]
	v_mfma_f32_16x16x32_bf16 v[14:17], v[142:145], v[194:197], v[14:17]
	v_mfma_f32_16x16x32_bf16 v[66:69], v[138:141], v[170:173], v[66:69]
	v_mfma_f32_16x16x32_bf16 v[62:65], v[146:149], v[170:173], v[62:65]
	v_mfma_f32_16x16x32_bf16 v[50:53], v[138:141], v[178:181], v[50:53]
	v_mfma_f32_16x16x32_bf16 v[46:49], v[146:149], v[178:181], v[46:49]
	v_mfma_f32_16x16x32_bf16 v[34:37], v[138:141], v[190:193], v[34:37]
	v_mfma_f32_16x16x32_bf16 v[30:33], v[146:149], v[190:193], v[30:33]
	v_mfma_f32_16x16x32_bf16 v[18:21], v[138:141], v[228:231], v[18:21]
	v_mfma_f32_16x16x32_bf16 v[14:17], v[146:149], v[228:231], v[14:17]
	s_setprio 0
	s_setprio 1
	v_mfma_f32_16x16x32_bf16 v[58:61], v[150:153], v[166:169], v[58:61]
	v_mfma_f32_16x16x32_bf16 v[54:57], v[158:161], v[166:169], v[54:57]
	v_mfma_f32_16x16x32_bf16 v[42:45], v[150:153], v[174:177], v[42:45]
	v_mfma_f32_16x16x32_bf16 v[38:41], v[158:161], v[174:177], v[38:41]
	v_mfma_f32_16x16x32_bf16 v[26:29], v[150:153], v[186:189], v[26:29]
	v_mfma_f32_16x16x32_bf16 v[22:25], v[158:161], v[186:189], v[22:25]
	v_mfma_f32_16x16x32_bf16 v[10:13], v[150:153], v[194:197], v[10:13]
	v_mfma_f32_16x16x32_bf16 v[4:7], v[158:161], v[194:197], v[6:9]
	v_mfma_f32_16x16x32_bf16 v[58:61], v[154:157], v[170:173], v[58:61]
	v_mfma_f32_16x16x32_bf16 v[54:57], v[162:165], v[170:173], v[54:57]
	s_barrier
	v_mfma_f32_16x16x32_bf16 v[42:45], v[154:157], v[178:181], v[42:45]
	v_mfma_f32_16x16x32_bf16 v[38:41], v[162:165], v[178:181], v[38:41]
	v_mfma_f32_16x16x32_bf16 v[26:29], v[154:157], v[190:193], v[26:29]
	v_mfma_f32_16x16x32_bf16 v[22:25], v[162:165], v[190:193], v[22:25]
	v_mfma_f32_16x16x32_bf16 v[10:13], v[154:157], v[228:231], v[10:13]
	v_mfma_f32_16x16x32_bf16 v[4:7], v[162:165], v[228:231], v[4:7]
	s_setprio 0
	s_add_i32 s54, 0, 0x18000
	v_add_u32_e32 v3, s54, v221
	s_add_i32 s55, 0, 0x1c000
	ds_read_b128 v[134:137], v3
	ds_read_b128 v[138:141], v3 offset:1024
	ds_read_b128 v[142:145], v3 offset:2048
	ds_read_b128 v[146:149], v3 offset:3072
	v_add_u32_e32 v3, s55, v221
	ds_read_b128 v[150:153], v3
	ds_read_b128 v[154:157], v3 offset:1024
	ds_read_b128 v[158:161], v3 offset:2048
	ds_read_b128 v[162:165], v3 offset:3072
	s_add_u32 s52, s70, 0x4000
	s_addc_u32 s53, s71, 0
	s_mov_b32 m0, s77
	v_lshl_add_u64 v[8:9], s[52:53], 0, v[198:199]
	ds_read_b128 v[166:169], v225 offset:32768
	ds_read_b128 v[170:173], v225 offset:33792
	ds_read_b128 v[174:177], v225 offset:34816
	ds_read_b128 v[178:181], v225 offset:35840
	ds_read_b128 v[186:189], v225 offset:36864
	ds_read_b128 v[190:193], v225 offset:37888
	ds_read_b128 v[194:197], v225 offset:38912
	ds_read_b128 v[228:231], v225 offset:39936
	global_load_lds_dwordx4 v[8:9], off
	v_lshl_add_u64 v[8:9], s[52:53], 0, v[202:203]
	s_mov_b32 m0, s78
	s_nop 0
	global_load_lds_dwordx4 v[8:9], off
	s_waitcnt vmcnt(8)
	s_waitcnt lgkmcnt(0)
	s_setprio 1
	s_barrier
	v_mfma_f32_16x16x32_bf16 v[130:133], v[134:137], v[166:169], v[130:133]
	v_mfma_f32_16x16x32_bf16 v[126:129], v[142:145], v[166:169], v[126:129]
	v_mfma_f32_16x16x32_bf16 v[114:117], v[134:137], v[174:177], v[114:117]
	v_mfma_f32_16x16x32_bf16 v[110:113], v[142:145], v[174:177], v[110:113]
	v_mfma_f32_16x16x32_bf16 v[98:101], v[134:137], v[186:189], v[98:101]
	v_mfma_f32_16x16x32_bf16 v[94:97], v[142:145], v[186:189], v[94:97]
	v_mfma_f32_16x16x32_bf16 v[82:85], v[134:137], v[194:197], v[82:85]
	v_mfma_f32_16x16x32_bf16 v[78:81], v[142:145], v[194:197], v[78:81]
	v_mfma_f32_16x16x32_bf16 v[130:133], v[138:141], v[170:173], v[130:133]
	v_mfma_f32_16x16x32_bf16 v[126:129], v[146:149], v[170:173], v[126:129]
	v_mfma_f32_16x16x32_bf16 v[114:117], v[138:141], v[178:181], v[114:117]
	v_mfma_f32_16x16x32_bf16 v[110:113], v[146:149], v[178:181], v[110:113]
	v_mfma_f32_16x16x32_bf16 v[98:101], v[138:141], v[190:193], v[98:101]
	v_mfma_f32_16x16x32_bf16 v[94:97], v[146:149], v[190:193], v[94:97]
	v_mfma_f32_16x16x32_bf16 v[82:85], v[138:141], v[228:231], v[82:85]
	v_mfma_f32_16x16x32_bf16 v[78:81], v[146:149], v[228:231], v[78:81]
	s_setprio 0
	s_setprio 1
	v_mfma_f32_16x16x32_bf16 v[122:125], v[150:153], v[166:169], v[122:125]
	v_mfma_f32_16x16x32_bf16 v[118:121], v[158:161], v[166:169], v[118:121]
	v_mfma_f32_16x16x32_bf16 v[106:109], v[150:153], v[174:177], v[106:109]
	v_mfma_f32_16x16x32_bf16 v[102:105], v[158:161], v[174:177], v[102:105]
	v_mfma_f32_16x16x32_bf16 v[90:93], v[150:153], v[186:189], v[90:93]
	v_mfma_f32_16x16x32_bf16 v[86:89], v[158:161], v[186:189], v[86:89]
	v_mfma_f32_16x16x32_bf16 v[74:77], v[150:153], v[194:197], v[74:77]
	v_mfma_f32_16x16x32_bf16 v[70:73], v[158:161], v[194:197], v[70:73]
	v_mfma_f32_16x16x32_bf16 v[122:125], v[154:157], v[170:173], v[122:125]
	v_mfma_f32_16x16x32_bf16 v[118:121], v[162:165], v[170:173], v[118:121]
	s_barrier
; #define PG8_STAGE(bufoff, gbase, voff) do { _Pragma("unroll") for (int _i = 0; _i < 2; ++_i) \
;         __builtin_amdgcn_global_load_lds((const unsigned*)((const char*)(gbase) + (voff)[_i]), (PG8_LAS unsigned*)(lds + (bufoff) + ldsw + _i * 8192), 16, 0, 0); } while (0)
; #define PG8_LDA(dst, b, h) do { _Pragma("unroll") for (int m = 0; m < 4; ++m) _Pragma("unroll") for (int k = 0; k < 2; ++k) dst[m][k] = *(const PG8_LAS bf16x8*)(lds + PG8_SA(b, h) + aoff + m * 2048 + k * 1024); } while (0)
; #define PG8_MMA(ai, bj, At, Bt) do { __builtin_amdgcn_s_setprio(1); _Pragma("unroll") for (int m = 0; m < 4; ++m) _Pragma("unroll") for (int n = 0; n < 2; ++n) _Pragma("unroll") for (int k = 0; k < 2; ++k) \
;         acc[ai][bj][m][n] = __builtin_amdgcn_mfma_f32_16x16x32_bf16(Bt[n][k], At[m][k], acc[ai][bj][m][n], 0, 0, 0); __builtin_amdgcn_s_setprio(0); } while (0)
; #define PG8_WAIT_V(n) asm volatile("s_waitcnt vmcnt(" #n ")" ::: "memory")
; #define PG8_WAIT_L(n) asm volatile("s_waitcnt lgkmcnt(" #n ")" ::: "memory")
; #define PG8_BAR __builtin_amdgcn_s_barrier()
; #define PG8_SCHED __builtin_amdgcn_sched_barrier(0)
; template <class Epi, class Sched, bool ALIGN_EPI = false, bool SP2 = false>
; __device__ __forceinline__ void gemm_phase(PG8_LAS unsigned char* lds, const Gemm g, const Sched& S, const Epi& E) {
;     ...
;             PG8_WAIT_V(8); PG8_WAIT_L(0); PG8_BAR; PG8_MMA(0, 0, At, B0); PG8_MMA(0, 1, At, B1); PG8_BAR; PG8_SCHED;
;             PG8_LDA(At, 1, 1); PG8_STAGE(PG8_SB(1, 0), b3, voffB); PG8_STAGE(PG8_SB(1, 1), b3 + hstepB, voffB); PG8_STAGE(PG8_SA(1, 0), a3, voffA);
;             PG8_WAIT_V(8); PG8_WAIT_L(0); PG8_BAR; PG8_MMA(1, 0, At, B0); PG8_MMA(1, 1, At, B1); PG8_BAR; PG8_SCHED;
	v_mfma_f32_16x16x32_bf16 v[106:109], v[154:157], v[178:181], v[106:109]
	v_mfma_f32_16x16x32_bf16 v[102:105], v[162:165], v[178:181], v[102:105]
	v_mfma_f32_16x16x32_bf16 v[90:93], v[154:157], v[190:193], v[90:93]
	v_mfma_f32_16x16x32_bf16 v[86:89], v[162:165], v[190:193], v[86:89]
	v_mfma_f32_16x16x32_bf16 v[74:77], v[154:157], v[228:231], v[74:77]
	v_mfma_f32_16x16x32_bf16 v[70:73], v[162:165], v[228:231], v[70:73]
	s_setprio 0
	s_add_u32 s52, s50, 0x8000
	s_addc_u32 s53, s51, 0
	s_add_i32 s54, s54, s73
	v_lshl_add_u64 v[8:9], s[52:53], 0, v[200:201]
	s_mov_b32 m0, s54
	ds_read_b128 v[166:169], v225 offset:49152
	ds_read_b128 v[170:173], v225 offset:50176
	ds_read_b128 v[174:177], v225 offset:51200
	ds_read_b128 v[178:181], v225 offset:52224
	ds_read_b128 v[186:189], v225 offset:53248
	ds_read_b128 v[190:193], v225 offset:54272
	ds_read_b128 v[194:197], v225 offset:55296
	ds_read_b128 v[228:231], v225 offset:56320
	global_load_lds_dwordx4 v[8:9], off
	s_add_i32 m0, s54, 0x2000
	s_add_u32 s50, s50, 0x9000
	v_lshl_add_u64 v[8:9], s[52:53], 0, v[204:205]
	s_addc_u32 s51, s51, 0
	s_add_i32 s52, s55, s73
	global_load_lds_dwordx4 v[8:9], off
	v_lshl_add_u64 v[8:9], s[50:51], 0, v[200:201]
	s_mov_b32 m0, s52
	s_nop 0
	global_load_lds_dwordx4 v[8:9], off
	v_lshl_add_u64 v[8:9], s[50:51], 0, v[204:205]
	s_add_i32 m0, s52, 0x2000
	s_nop 0
	global_load_lds_dwordx4 v[8:9], off
	v_lshl_add_u64 v[8:9], s[48:49], 0, v[198:199]
	s_mov_b32 m0, s81
	s_nop 0
	global_load_lds_dwordx4 v[8:9], off
	v_lshl_add_u64 v[8:9], s[48:49], 0, v[202:203]
	s_mov_b32 m0, s82
	s_nop 0
	global_load_lds_dwordx4 v[8:9], off
	s_waitcnt vmcnt(8)
	s_waitcnt lgkmcnt(0)
	s_setprio 1
	s_barrier
	v_mfma_f32_16x16x32_bf16 v[66:69], v[134:137], v[166:169], v[66:69]
	v_mfma_f32_16x16x32_bf16 v[62:65], v[142:145], v[166:169], v[62:65]
	v_mfma_f32_16x16x32_bf16 v[50:53], v[134:137], v[174:177], v[50:53]
	v_mfma_f32_16x16x32_bf16 v[46:49], v[142:145], v[174:177], v[46:49]
	v_mfma_f32_16x16x32_bf16 v[34:37], v[134:137], v[186:189], v[34:37]
	v_mfma_f32_16x16x32_bf16 v[30:33], v[142:145], v[186:189], v[30:33]
	v_mfma_f32_16x16x32_bf16 v[18:21], v[134:137], v[194:197], v[18:21]
	v_mfma_f32_16x16x32_bf16 v[14:17], v[142:145], v[194:197], v[14:17]
	v_mfma_f32_16x16x32_bf16 v[66:69], v[138:141], v[170:173], v[66:69]
	v_mfma_f32_16x16x32_bf16 v[62:65], v[146:149], v[170:173], v[62:65]
	v_mfma_f32_16x16x32_bf16 v[50:53], v[138:141], v[178:181], v[50:53]
	v_mfma_f32_16x16x32_bf16 v[46:49], v[146:149], v[178:181], v[46:49]
	v_mfma_f32_16x16x32_bf16 v[34:37], v[138:141], v[190:193], v[34:37]
	v_mfma_f32_16x16x32_bf16 v[30:33], v[146:149], v[190:193], v[30:33]
	v_mfma_f32_16x16x32_bf16 v[18:21], v[138:141], v[228:231], v[18:21]
	v_mfma_f32_16x16x32_bf16 v[14:17], v[146:149], v[228:231], v[14:17]
	s_setprio 0
	s_setprio 1
	v_mfma_f32_16x16x32_bf16 v[58:61], v[150:153], v[166:169], v[58:61]
	v_mfma_f32_16x16x32_bf16 v[54:57], v[158:161], v[166:169], v[54:57]
	v_mfma_f32_16x16x32_bf16 v[42:45], v[150:153], v[174:177], v[42:45]
	v_mfma_f32_16x16x32_bf16 v[38:41], v[158:161], v[174:177], v[38:41]
	v_mfma_f32_16x16x32_bf16 v[26:29], v[150:153], v[186:189], v[26:29]
	v_mfma_f32_16x16x32_bf16 v[22:25], v[158:161], v[186:189], v[22:25]
	v_mfma_f32_16x16x32_bf16 v[8:11], v[150:153], v[194:197], v[10:13]
	v_mfma_f32_16x16x32_bf16 v[4:7], v[158:161], v[194:197], v[4:7]
	v_mfma_f32_16x16x32_bf16 v[58:61], v[154:157], v[170:173], v[58:61]
	v_mfma_f32_16x16x32_bf16 v[54:57], v[162:165], v[170:173], v[54:57]
	s_barrier
	v_mfma_f32_16x16x32_bf16 v[42:45], v[154:157], v[178:181], v[42:45]
	v_mfma_f32_16x16x32_bf16 v[38:41], v[162:165], v[178:181], v[38:41]
	v_mfma_f32_16x16x32_bf16 v[26:29], v[154:157], v[190:193], v[26:29]
	v_mfma_f32_16x16x32_bf16 v[22:25], v[162:165], v[190:193], v[22:25]
	v_mfma_f32_16x16x32_bf16 v[10:13], v[154:157], v[228:231], v[8:11]
	v_mfma_f32_16x16x32_bf16 v[6:9], v[162:165], v[228:231], v[4:7]
	s_setprio 0
	s_add_i32 s56, s56, 2
	s_add_u32 s46, s46, 0x10000
	s_addc_u32 s47, s47, 0
	s_cmp_gt_u32 s56, 13
	s_cbranch_scc1 .LBB0_383

; #define PG8_STAGE(bufoff, gbase, voff) do { _Pragma("unroll") for (int _i = 0; _i < 2; ++_i) \
;         __builtin_amdgcn_global_load_lds((const unsigned*)((const char*)(gbase) + (voff)[_i]), (PG8_LAS unsigned*)(lds + (bufoff) + ldsw + _i * 8192), 16, 0, 0); } while (0)
; #define PG8_LDA(dst, b, h) do { _Pragma("unroll") for (int m = 0; m < 4; ++m) _Pragma("unroll") for (int k = 0; k < 2; ++k) dst[m][k] = *(const PG8_LAS bf16x8*)(lds + PG8_SA(b, h) + aoff + m * 2048 + k * 1024); } while (0)
; #define PG8_LDB(dst, b, h) do { _Pragma("unroll") for (int n = 0; n < 2; ++n) _Pragma("unroll") for (int k = 0; k < 2; ++k) dst[n][k] = *(const PG8_LAS bf16x8*)(lds + PG8_SB(b, h) + boff + n * 2048 + k * 1024); } while (0)
; #define PG8_MMA(ai, bj, At, Bt) do { __builtin_amdgcn_s_setprio(1); _Pragma("unroll") for (int m = 0; m < 4; ++m) _Pragma("unroll") for (int n = 0; n < 2; ++n) _Pragma("unroll") for (int k = 0; k < 2; ++k) \
;         acc[ai][bj][m][n] = __builtin_amdgcn_mfma_f32_16x16x32_bf16(Bt[n][k], At[m][k], acc[ai][bj][m][n], 0, 0, 0); __builtin_amdgcn_s_setprio(0); } while (0)
; #define PG8_WAIT_V(n) asm volatile("s_waitcnt vmcnt(" #n ")" ::: "memory")
; #define PG8_WAIT_L(n) asm volatile("s_waitcnt lgkmcnt(" #n ")" ::: "memory")
; #define PG8_BAR __builtin_amdgcn_s_barrier()
; #define PG8_SCHED __builtin_amdgcn_sched_barrier(0)
; template <class Epi, class Sched, bool ALIGN_EPI = false, bool SP2 = false>
; __device__ __forceinline__ void gemm_phase(PG8_LAS unsigned char* lds, const Gemm g, const Sched& S, const Epi& E) {
;     ...
;             const bool last = (t == nt - 2);
;             const char* a1 = cA + (size_t)(t + 1) * kstep;
;             const char* a2 = last ? nA : cA + (size_t)(t + 2) * kstep; const char* b2 = last ? nB : cB + (size_t)(t + 2) * kstep;
;             const char* a3 = a2 + kstep; const char* b3 = b2 + kstep;
;             if (last && has_next) S.a_ready(nxt);
;             if constexpr (SP2) {
;             PG8_LDB(B0, 0, 0); PG8_LDB(B1, 0, 1); PG8_SCHED; PG8_LDA(At, 0, 0); PG8_STAGE(PG8_SA(1, 1), a1 + hstep, voffA);
;             PG8_WAIT_V(8); PG8_WAIT_L(0); PG8_BAR; PG8_MMA(0, 0, At, B0); PG8_MMA(0, 1, At, B1); PG8_BAR; PG8_SCHED;
;             PG8_LDA(At, 0, 1); PG8_STAGE(PG8_SB(0, 0), b2, voffB); PG8_STAGE(PG8_SB(0, 1), b2 + hstepB, voffB); PG8_STAGE(PG8_SA(0, 0), a2, voffA);
.LBB0_477:
	ds_read_b128 v[130:133], v201
	ds_read_b128 v[134:137], v201 offset:1024
	ds_read_b128 v[138:141], v201 offset:2048
	ds_read_b128 v[142:145], v201 offset:3072
	ds_read_b128 v[146:149], v202
	ds_read_b128 v[150:153], v202 offset:1024
	ds_read_b128 v[154:157], v202 offset:2048
	ds_read_b128 v[158:161], v202 offset:3072
	s_add_u32 s68, s50, 0x4000
	s_addc_u32 s69, s51, 0
	s_cmp_eq_u32 s55, 12
	s_cselect_b32 s72, s47, s68
	s_cselect_b32 s73, s29, s69
	s_cselect_b32 s70, s52, s53
	s_cselect_b32 s71, s27, s54
	s_add_u32 s68, s72, 0x8000
	s_addc_u32 s69, s73, 0
	v_lshl_add_u64 v[196:197], s[50:51], 0, v[188:189]
	s_add_i32 m0, s1, 0xc000
	ds_read_b128 v[162:165], v203
	ds_read_b128 v[166:169], v203 offset:1024
	ds_read_b128 v[170:173], v203 offset:2048
	ds_read_b128 v[174:177], v203 offset:3072
	ds_read_b128 v[208:211], v203 offset:4096
	ds_read_b128 v[212:215], v203 offset:5120
	ds_read_b128 v[220:223], v203 offset:6144
	ds_read_b128 v[224:227], v203 offset:7168
	global_load_lds_dwordx4 v[196:197], off
	v_lshl_add_u64 v[196:197], s[50:51], 0, v[190:191]
	s_add_i32 m0, s1, 0xe000
	s_nop 0
	global_load_lds_dwordx4 v[196:197], off
	s_waitcnt vmcnt(8)
	s_waitcnt lgkmcnt(0)
	s_setprio 1
	s_barrier
	v_mfma_f32_16x16x32_bf16 v[126:129], v[130:133], v[162:165], v[126:129]
	v_mfma_f32_16x16x32_bf16 v[122:125], v[138:141], v[162:165], v[122:125]
	v_mfma_f32_16x16x32_bf16 v[110:113], v[130:133], v[170:173], v[110:113]
	v_mfma_f32_16x16x32_bf16 v[106:109], v[138:141], v[170:173], v[106:109]
	v_mfma_f32_16x16x32_bf16 v[94:97], v[130:133], v[208:211], v[94:97]
	v_mfma_f32_16x16x32_bf16 v[90:93], v[138:141], v[208:211], v[90:93]
	v_mfma_f32_16x16x32_bf16 v[78:81], v[130:133], v[220:223], v[78:81]
	v_mfma_f32_16x16x32_bf16 v[74:77], v[138:141], v[220:223], v[74:77]
	v_mfma_f32_16x16x32_bf16 v[126:129], v[134:137], v[166:169], v[126:129]
	v_mfma_f32_16x16x32_bf16 v[122:125], v[142:145], v[166:169], v[122:125]
	v_mfma_f32_16x16x32_bf16 v[110:113], v[134:137], v[174:177], v[110:113]
	v_mfma_f32_16x16x32_bf16 v[106:109], v[142:145], v[174:177], v[106:109]
	v_mfma_f32_16x16x32_bf16 v[94:97], v[134:137], v[212:215], v[94:97]
	v_mfma_f32_16x16x32_bf16 v[90:93], v[142:145], v[212:215], v[90:93]
	v_mfma_f32_16x16x32_bf16 v[78:81], v[134:137], v[224:227], v[78:81]
	v_mfma_f32_16x16x32_bf16 v[74:77], v[142:145], v[224:227], v[74:77]
	s_setprio 0
	s_setprio 1
	v_mfma_f32_16x16x32_bf16 v[118:121], v[146:149], v[162:165], v[118:121]
	v_mfma_f32_16x16x32_bf16 v[114:117], v[154:157], v[162:165], v[114:117]
	v_mfma_f32_16x16x32_bf16 v[102:105], v[146:149], v[170:173], v[102:105]
	v_mfma_f32_16x16x32_bf16 v[98:101], v[154:157], v[170:173], v[98:101]
	v_mfma_f32_16x16x32_bf16 v[86:89], v[146:149], v[208:211], v[86:89]
	v_mfma_f32_16x16x32_bf16 v[82:85], v[154:157], v[208:211], v[82:85]
	v_mfma_f32_16x16x32_bf16 v[70:73], v[146:149], v[220:223], v[70:73]
	v_mfma_f32_16x16x32_bf16 v[66:69], v[154:157], v[220:223], v[66:69]
	v_mfma_f32_16x16x32_bf16 v[118:121], v[150:153], v[166:169], v[118:121]
	v_mfma_f32_16x16x32_bf16 v[114:117], v[158:161], v[166:169], v[114:117]
	s_barrier
	v_mfma_f32_16x16x32_bf16 v[102:105], v[150:153], v[174:177], v[102:105]
	v_mfma_f32_16x16x32_bf16 v[98:101], v[158:161], v[174:177], v[98:101]
	v_mfma_f32_16x16x32_bf16 v[86:89], v[150:153], v[212:215], v[86:89]
	v_mfma_f32_16x16x32_bf16 v[82:85], v[158:161], v[212:215], v[82:85]
	v_mfma_f32_16x16x32_bf16 v[70:73], v[150:153], v[224:227], v[70:73]
	v_mfma_f32_16x16x32_bf16 v[66:69], v[158:161], v[224:227], v[66:69]
	s_setprio 0
	s_add_i32 s79, s77, s0
	v_lshl_add_u64 v[196:197], s[70:71], 0, v[180:181]
	s_mov_b32 m0, s79
	ds_read_b128 v[162:165], v203 offset:16384
	ds_read_b128 v[166:169], v203 offset:17408
	ds_read_b128 v[170:173], v203 offset:18432
	ds_read_b128 v[174:177], v203 offset:19456
	ds_read_b128 v[208:211], v203 offset:20480
	ds_read_b128 v[212:215], v203 offset:21504
	ds_read_b128 v[220:223], v203 offset:22528
	ds_read_b128 v[224:227], v203 offset:23552
	global_load_lds_dwordx4 v[196:197], off
	s_add_i32 m0, s79, 0x2000
	s_add_u32 s80, s70, 0x1000
	v_lshl_add_u64 v[196:197], s[70:71], 0, v[184:185]
	s_addc_u32 s81, s71, 0
	s_add_i32 s79, s78, s0
	global_load_lds_dwordx4 v[196:197], off
	v_lshl_add_u64 v[196:197], s[80:81], 0, v[180:181]
	s_mov_b32 m0, s79
	s_nop 0
	global_load_lds_dwordx4 v[196:197], off
	v_lshl_add_u64 v[196:197], s[80:81], 0, v[184:185]
	s_add_i32 m0, s79, 0x2000
	s_nop 0
	global_load_lds_dwordx4 v[196:197], off
	v_lshl_add_u64 v[196:197], s[72:73], 0, v[178:179]
	s_mov_b32 m0, s1
	s_nop 0
	global_load_lds_dwordx4 v[196:197], off
	v_lshl_add_u64 v[196:197], s[72:73], 0, v[182:183]
	s_mov_b32 m0, s49
	s_nop 0
	global_load_lds_dwordx4 v[196:197], off
	s_waitcnt vmcnt(8)
	s_waitcnt lgkmcnt(0)
	s_setprio 1
	s_barrier
; #define PG8_STAGE(bufoff, gbase, voff) do { _Pragma("unroll") for (int _i = 0; _i < 2; ++_i) \
;         __builtin_amdgcn_global_load_lds((const unsigned*)((const char*)(gbase) + (voff)[_i]), (PG8_LAS unsigned*)(lds + (bufoff) + ldsw + _i * 8192), 16, 0, 0); } while (0)
; #define PG8_LDA(dst, b, h) do { _Pragma("unroll") for (int m = 0; m < 4; ++m) _Pragma("unroll") for (int k = 0; k < 2; ++k) dst[m][k] = *(const PG8_LAS bf16x8*)(lds + PG8_SA(b, h) + aoff + m * 2048 + k * 1024); } while (0)
; #define PG8_LDB(dst, b, h) do { _Pragma("unroll") for (int n = 0; n < 2; ++n) _Pragma("unroll") for (int k = 0; k < 2; ++k) dst[n][k] = *(const PG8_LAS bf16x8*)(lds + PG8_SB(b, h) + boff + n * 2048 + k * 1024); } while (0)
; #define PG8_MMA(ai, bj, At, Bt) do { __builtin_amdgcn_s_setprio(1); _Pragma("unroll") for (int m = 0; m < 4; ++m) _Pragma("unroll") for (int n = 0; n < 2; ++n) _Pragma("unroll") for (int k = 0; k < 2; ++k) \
;         acc[ai][bj][m][n] = __builtin_amdgcn_mfma_f32_16x16x32_bf16(Bt[n][k], At[m][k], acc[ai][bj][m][n], 0, 0, 0); __builtin_amdgcn_s_setprio(0); } while (0)
; #define PG8_WAIT_V(n) asm volatile("s_waitcnt vmcnt(" #n ")" ::: "memory")
; #define PG8_WAIT_L(n) asm volatile("s_waitcnt lgkmcnt(" #n ")" ::: "memory")
; #define PG8_BAR __builtin_amdgcn_s_barrier()
; #define PG8_SCHED __builtin_amdgcn_sched_barrier(0)
; template <class Epi, class Sched, bool ALIGN_EPI = false, bool SP2 = false>
; __device__ __forceinline__ void gemm_phase(PG8_LAS unsigned char* lds, const Gemm g, const Sched& S, const Epi& E) {
;     ...
;             PG8_LDA(At, 0, 1); PG8_STAGE(PG8_SB(0, 0), b2, voffB); PG8_STAGE(PG8_SB(0, 1), b2 + hstepB, voffB); PG8_STAGE(PG8_SA(0, 0), a2, voffA);
;             PG8_WAIT_V(8); PG8_WAIT_L(0); PG8_BAR; PG8_MMA(1, 0, At, B0); PG8_MMA(1, 1, At, B1); PG8_BAR; PG8_SCHED;
;             PG8_LDB(B0, 1, 0); PG8_LDB(B1, 1, 1); PG8_SCHED; PG8_LDA(At, 1, 0); PG8_STAGE(PG8_SA(0, 1), a2 + hstep, voffA);
;             PG8_WAIT_V(8); PG8_WAIT_L(0); PG8_BAR; PG8_MMA(0, 0, At, B0); PG8_MMA(0, 1, At, B1); PG8_BAR; PG8_SCHED;
	v_mfma_f32_16x16x32_bf16 v[62:65], v[130:133], v[162:165], v[62:65]
	v_mfma_f32_16x16x32_bf16 v[58:61], v[138:141], v[162:165], v[58:61]
	v_mfma_f32_16x16x32_bf16 v[46:49], v[130:133], v[170:173], v[46:49]
	v_mfma_f32_16x16x32_bf16 v[42:45], v[138:141], v[170:173], v[42:45]
	v_mfma_f32_16x16x32_bf16 v[30:33], v[130:133], v[208:211], v[30:33]
	v_mfma_f32_16x16x32_bf16 v[26:29], v[138:141], v[208:211], v[26:29]
	v_mfma_f32_16x16x32_bf16 v[14:17], v[130:133], v[220:223], v[14:17]
	v_mfma_f32_16x16x32_bf16 v[10:13], v[138:141], v[220:223], v[10:13]
	v_mfma_f32_16x16x32_bf16 v[62:65], v[134:137], v[166:169], v[62:65]
	v_mfma_f32_16x16x32_bf16 v[58:61], v[142:145], v[166:169], v[58:61]
	v_mfma_f32_16x16x32_bf16 v[46:49], v[134:137], v[174:177], v[46:49]
	v_mfma_f32_16x16x32_bf16 v[42:45], v[142:145], v[174:177], v[42:45]
	v_mfma_f32_16x16x32_bf16 v[30:33], v[134:137], v[212:215], v[30:33]
	v_mfma_f32_16x16x32_bf16 v[26:29], v[142:145], v[212:215], v[26:29]
	v_mfma_f32_16x16x32_bf16 v[14:17], v[134:137], v[224:227], v[14:17]
	v_mfma_f32_16x16x32_bf16 v[10:13], v[142:145], v[224:227], v[10:13]
	s_setprio 0
	s_setprio 1
	v_mfma_f32_16x16x32_bf16 v[54:57], v[146:149], v[162:165], v[54:57]
	v_mfma_f32_16x16x32_bf16 v[50:53], v[154:157], v[162:165], v[50:53]
	v_mfma_f32_16x16x32_bf16 v[38:41], v[146:149], v[170:173], v[38:41]
	v_mfma_f32_16x16x32_bf16 v[34:37], v[154:157], v[170:173], v[34:37]
	v_mfma_f32_16x16x32_bf16 v[22:25], v[146:149], v[208:211], v[22:25]
	v_mfma_f32_16x16x32_bf16 v[18:21], v[154:157], v[208:211], v[18:21]
	v_mfma_f32_16x16x32_bf16 v[6:9], v[146:149], v[220:223], v[6:9]
	v_mfma_f32_16x16x32_bf16 v[2:5], v[154:157], v[220:223], v[2:5]
	v_mfma_f32_16x16x32_bf16 v[54:57], v[150:153], v[166:169], v[54:57]
	v_mfma_f32_16x16x32_bf16 v[50:53], v[158:161], v[166:169], v[50:53]
	s_barrier
	v_mfma_f32_16x16x32_bf16 v[38:41], v[150:153], v[174:177], v[38:41]
	v_mfma_f32_16x16x32_bf16 v[34:37], v[158:161], v[174:177], v[34:37]
	v_mfma_f32_16x16x32_bf16 v[22:25], v[150:153], v[212:215], v[22:25]
	v_mfma_f32_16x16x32_bf16 v[18:21], v[158:161], v[212:215], v[18:21]
	v_mfma_f32_16x16x32_bf16 v[6:9], v[150:153], v[224:227], v[6:9]
	v_mfma_f32_16x16x32_bf16 v[2:5], v[158:161], v[224:227], v[2:5]
	s_setprio 0
	s_add_i32 s79, 0, 0x18000
	s_add_i32 s80, 0, 0x1c000
	v_add_u32_e32 v142, s79, v199
	v_add_u32_e32 v158, s80, v199
	ds_read_b128 v[130:133], v142
	ds_read_b128 v[134:137], v142 offset:1024
	ds_read_b128 v[138:141], v142 offset:2048
	ds_read_b128 v[142:145], v142 offset:3072
	ds_read_b128 v[146:149], v158
	ds_read_b128 v[150:153], v158 offset:1024
	ds_read_b128 v[154:157], v158 offset:2048
	ds_read_b128 v[158:161], v158 offset:3072
	s_add_u32 s72, s72, 0x4000
	s_addc_u32 s73, s73, 0
	s_mov_b32 m0, s56
	v_lshl_add_u64 v[196:197], s[72:73], 0, v[178:179]
	ds_read_b128 v[162:165], v203 offset:32768
	ds_read_b128 v[166:169], v203 offset:33792
	ds_read_b128 v[170:173], v203 offset:34816
	ds_read_b128 v[174:177], v203 offset:35840
	ds_read_b128 v[208:211], v203 offset:36864
	ds_read_b128 v[212:215], v203 offset:37888
	ds_read_b128 v[220:223], v203 offset:38912
	ds_read_b128 v[224:227], v203 offset:39936
	global_load_lds_dwordx4 v[196:197], off
	v_lshl_add_u64 v[196:197], s[72:73], 0, v[182:183]
	s_mov_b32 m0, s57
	s_nop 0
	global_load_lds_dwordx4 v[196:197], off
	s_waitcnt vmcnt(8)
	s_waitcnt lgkmcnt(0)
	s_setprio 1
	s_barrier
	v_mfma_f32_16x16x32_bf16 v[126:129], v[130:133], v[162:165], v[126:129]
	v_mfma_f32_16x16x32_bf16 v[122:125], v[138:141], v[162:165], v[122:125]
	v_mfma_f32_16x16x32_bf16 v[110:113], v[130:133], v[170:173], v[110:113]
	v_mfma_f32_16x16x32_bf16 v[106:109], v[138:141], v[170:173], v[106:109]
	v_mfma_f32_16x16x32_bf16 v[94:97], v[130:133], v[208:211], v[94:97]
	v_mfma_f32_16x16x32_bf16 v[90:93], v[138:141], v[208:211], v[90:93]
	v_mfma_f32_16x16x32_bf16 v[78:81], v[130:133], v[220:223], v[78:81]
	v_mfma_f32_16x16x32_bf16 v[74:77], v[138:141], v[220:223], v[74:77]
	v_mfma_f32_16x16x32_bf16 v[126:129], v[134:137], v[166:169], v[126:129]
	v_mfma_f32_16x16x32_bf16 v[122:125], v[142:145], v[166:169], v[122:125]
	v_mfma_f32_16x16x32_bf16 v[110:113], v[134:137], v[174:177], v[110:113]
	v_mfma_f32_16x16x32_bf16 v[106:109], v[142:145], v[174:177], v[106:109]
	v_mfma_f32_16x16x32_bf16 v[94:97], v[134:137], v[212:215], v[94:97]
	v_mfma_f32_16x16x32_bf16 v[90:93], v[142:145], v[212:215], v[90:93]
	v_mfma_f32_16x16x32_bf16 v[78:81], v[134:137], v[224:227], v[78:81]
	v_mfma_f32_16x16x32_bf16 v[74:77], v[142:145], v[224:227], v[74:77]
	s_setprio 0
	s_setprio 1
	v_mfma_f32_16x16x32_bf16 v[118:121], v[146:149], v[162:165], v[118:121]
	v_mfma_f32_16x16x32_bf16 v[114:117], v[154:157], v[162:165], v[114:117]
	v_mfma_f32_16x16x32_bf16 v[102:105], v[146:149], v[170:173], v[102:105]
	v_mfma_f32_16x16x32_bf16 v[98:101], v[154:157], v[170:173], v[98:101]
	v_mfma_f32_16x16x32_bf16 v[86:89], v[146:149], v[208:211], v[86:89]
	v_mfma_f32_16x16x32_bf16 v[82:85], v[154:157], v[208:211], v[82:85]
	v_mfma_f32_16x16x32_bf16 v[70:73], v[146:149], v[220:223], v[70:73]
	v_mfma_f32_16x16x32_bf16 v[66:69], v[154:157], v[220:223], v[66:69]
	v_mfma_f32_16x16x32_bf16 v[118:121], v[150:153], v[166:169], v[118:121]
	v_mfma_f32_16x16x32_bf16 v[114:117], v[158:161], v[166:169], v[114:117]
	s_barrier
; #define PG8_STAGE(bufoff, gbase, voff) do { _Pragma("unroll") for (int _i = 0; _i < 2; ++_i) \
;         __builtin_amdgcn_global_load_lds((const unsigned*)((const char*)(gbase) + (voff)[_i]), (PG8_LAS unsigned*)(lds + (bufoff) + ldsw + _i * 8192), 16, 0, 0); } while (0)
; #define PG8_LDA(dst, b, h) do { _Pragma("unroll") for (int m = 0; m < 4; ++m) _Pragma("unroll") for (int k = 0; k < 2; ++k) dst[m][k] = *(const PG8_LAS bf16x8*)(lds + PG8_SA(b, h) + aoff + m * 2048 + k * 1024); } while (0)
; #define PG8_MMA(ai, bj, At, Bt) do { __builtin_amdgcn_s_setprio(1); _Pragma("unroll") for (int m = 0; m < 4; ++m) _Pragma("unroll") for (int n = 0; n < 2; ++n) _Pragma("unroll") for (int k = 0; k < 2; ++k) \
;         acc[ai][bj][m][n] = __builtin_amdgcn_mfma_f32_16x16x32_bf16(Bt[n][k], At[m][k], acc[ai][bj][m][n], 0, 0, 0); __builtin_amdgcn_s_setprio(0); } while (0)
; #define PG8_WAIT_V(n) asm volatile("s_waitcnt vmcnt(" #n ")" ::: "memory")
; #define PG8_WAIT_L(n) asm volatile("s_waitcnt lgkmcnt(" #n ")" ::: "memory")
; #define PG8_BAR __builtin_amdgcn_s_barrier()
; #define PG8_SCHED __builtin_amdgcn_sched_barrier(0)
; template <class Epi, class Sched, bool ALIGN_EPI = false, bool SP2 = false>
; __device__ __forceinline__ void gemm_phase(PG8_LAS unsigned char* lds, const Gemm g, const Sched& S, const Epi& E) {
;     ...
;             PG8_WAIT_V(8); PG8_WAIT_L(0); PG8_BAR; PG8_MMA(0, 0, At, B0); PG8_MMA(0, 1, At, B1); PG8_BAR; PG8_SCHED;
;             PG8_LDA(At, 1, 1); PG8_STAGE(PG8_SB(1, 0), b3, voffB); PG8_STAGE(PG8_SB(1, 1), b3 + hstepB, voffB); PG8_STAGE(PG8_SA(1, 0), a3, voffA);
;             PG8_WAIT_V(8); PG8_WAIT_L(0); PG8_BAR; PG8_MMA(1, 0, At, B0); PG8_MMA(1, 1, At, B1); PG8_BAR; PG8_SCHED;
;     ...
;         if constexpr (ALIGN_EPI) { if (wr == 0) PG8_BAR; }
	v_mfma_f32_16x16x32_bf16 v[102:105], v[150:153], v[174:177], v[102:105]
	v_mfma_f32_16x16x32_bf16 v[98:101], v[158:161], v[174:177], v[98:101]
	v_mfma_f32_16x16x32_bf16 v[86:89], v[150:153], v[212:215], v[86:89]
	v_mfma_f32_16x16x32_bf16 v[82:85], v[158:161], v[212:215], v[82:85]
	v_mfma_f32_16x16x32_bf16 v[70:73], v[150:153], v[224:227], v[70:73]
	v_mfma_f32_16x16x32_bf16 v[66:69], v[158:161], v[224:227], v[66:69]
	s_setprio 0
	s_add_u32 s72, s70, 0x8000
	s_addc_u32 s73, s71, 0
	s_add_i32 s79, s79, s0
	v_lshl_add_u64 v[196:197], s[72:73], 0, v[180:181]
	s_mov_b32 m0, s79
	ds_read_b128 v[162:165], v203 offset:49152
	ds_read_b128 v[166:169], v203 offset:50176
	ds_read_b128 v[170:173], v203 offset:51200
	ds_read_b128 v[174:177], v203 offset:52224
	ds_read_b128 v[208:211], v203 offset:53248
	ds_read_b128 v[212:215], v203 offset:54272
	ds_read_b128 v[220:223], v203 offset:55296
	ds_read_b128 v[224:227], v203 offset:56320
	global_load_lds_dwordx4 v[196:197], off
	s_add_i32 m0, s79, 0x2000
	s_add_u32 s70, s70, 0x9000
	v_lshl_add_u64 v[196:197], s[72:73], 0, v[184:185]
	s_addc_u32 s71, s71, 0
	s_add_i32 s72, s80, s0
	global_load_lds_dwordx4 v[196:197], off
	v_lshl_add_u64 v[196:197], s[70:71], 0, v[180:181]
	s_mov_b32 m0, s72
	s_nop 0
	global_load_lds_dwordx4 v[196:197], off
	v_lshl_add_u64 v[196:197], s[70:71], 0, v[184:185]
	s_add_i32 m0, s72, 0x2000
	s_nop 0
	global_load_lds_dwordx4 v[196:197], off
	v_lshl_add_u64 v[196:197], s[68:69], 0, v[178:179]
	s_mov_b32 m0, s59
	s_nop 0
	global_load_lds_dwordx4 v[196:197], off
	v_lshl_add_u64 v[196:197], s[68:69], 0, v[182:183]
	s_mov_b32 m0, s74
	s_nop 0
	global_load_lds_dwordx4 v[196:197], off
	s_waitcnt vmcnt(8)
	s_waitcnt lgkmcnt(0)
	s_setprio 1
	s_barrier
	v_mfma_f32_16x16x32_bf16 v[62:65], v[130:133], v[162:165], v[62:65]
	v_mfma_f32_16x16x32_bf16 v[58:61], v[138:141], v[162:165], v[58:61]
	v_mfma_f32_16x16x32_bf16 v[46:49], v[130:133], v[170:173], v[46:49]
	v_mfma_f32_16x16x32_bf16 v[42:45], v[138:141], v[170:173], v[42:45]
	v_mfma_f32_16x16x32_bf16 v[30:33], v[130:133], v[208:211], v[30:33]
	v_mfma_f32_16x16x32_bf16 v[26:29], v[138:141], v[208:211], v[26:29]
	v_mfma_f32_16x16x32_bf16 v[14:17], v[130:133], v[220:223], v[14:17]
	v_mfma_f32_16x16x32_bf16 v[10:13], v[138:141], v[220:223], v[10:13]
	v_mfma_f32_16x16x32_bf16 v[62:65], v[134:137], v[166:169], v[62:65]
	v_mfma_f32_16x16x32_bf16 v[58:61], v[142:145], v[166:169], v[58:61]
	v_mfma_f32_16x16x32_bf16 v[46:49], v[134:137], v[174:177], v[46:49]
	v_mfma_f32_16x16x32_bf16 v[42:45], v[142:145], v[174:177], v[42:45]
	v_mfma_f32_16x16x32_bf16 v[30:33], v[134:137], v[212:215], v[30:33]
	v_mfma_f32_16x16x32_bf16 v[26:29], v[142:145], v[212:215], v[26:29]
	v_mfma_f32_16x16x32_bf16 v[14:17], v[134:137], v[224:227], v[14:17]
	v_mfma_f32_16x16x32_bf16 v[10:13], v[142:145], v[224:227], v[10:13]
	s_setprio 0
	s_setprio 1
	v_mfma_f32_16x16x32_bf16 v[54:57], v[146:149], v[162:165], v[54:57]
	v_mfma_f32_16x16x32_bf16 v[50:53], v[154:157], v[162:165], v[50:53]
	v_mfma_f32_16x16x32_bf16 v[38:41], v[146:149], v[170:173], v[38:41]
	v_mfma_f32_16x16x32_bf16 v[34:37], v[154:157], v[170:173], v[34:37]
	v_mfma_f32_16x16x32_bf16 v[22:25], v[146:149], v[208:211], v[22:25]
	v_mfma_f32_16x16x32_bf16 v[18:21], v[154:157], v[208:211], v[18:21]
	v_mfma_f32_16x16x32_bf16 v[6:9], v[146:149], v[220:223], v[6:9]
	v_mfma_f32_16x16x32_bf16 v[2:5], v[154:157], v[220:223], v[2:5]
	v_mfma_f32_16x16x32_bf16 v[54:57], v[150:153], v[166:169], v[54:57]
	v_mfma_f32_16x16x32_bf16 v[50:53], v[158:161], v[166:169], v[50:53]
	s_barrier
	v_mfma_f32_16x16x32_bf16 v[38:41], v[150:153], v[174:177], v[38:41]
	v_mfma_f32_16x16x32_bf16 v[34:37], v[158:161], v[174:177], v[34:37]
	v_mfma_f32_16x16x32_bf16 v[22:25], v[150:153], v[212:215], v[22:25]
	v_mfma_f32_16x16x32_bf16 v[18:21], v[158:161], v[212:215], v[18:21]
	v_mfma_f32_16x16x32_bf16 v[6:9], v[150:153], v[224:227], v[6:9]
	v_mfma_f32_16x16x32_bf16 v[2:5], v[158:161], v[224:227], v[2:5]
	s_setprio 0
	s_add_i32 s55, s55, 2
	s_add_u32 s50, s50, 0x10000
	s_addc_u32 s51, s51, 0
	s_add_u32 s53, s53, 0x10000
	s_addc_u32 s54, s54, 0
	s_cmp_gt_u32 s55, 13
	s_cbranch_scc0 .LBB0_477
	s_and_b64 vcc, exec, s[14:15]
	s_cbranch_vccz .LBB0_480
	s_barrier

; #define PG8_STAGE(bufoff, gbase, voff) do { _Pragma("unroll") for (int _i = 0; _i < 2; ++_i) \
;         __builtin_amdgcn_global_load_lds((const unsigned*)((const char*)(gbase) + (voff)[_i]), (PG8_LAS unsigned*)(lds + (bufoff) + ldsw + _i * 8192), 16, 0, 0); } while (0)
; #define PG8_LDA(dst, b, h) do { _Pragma("unroll") for (int m = 0; m < 4; ++m) _Pragma("unroll") for (int k = 0; k < 2; ++k) dst[m][k] = *(const PG8_LAS bf16x8*)(lds + PG8_SA(b, h) + aoff + m * 2048 + k * 1024); } while (0)
; #define PG8_LDB(dst, b, h) do { _Pragma("unroll") for (int n = 0; n < 2; ++n) _Pragma("unroll") for (int k = 0; k < 2; ++k) dst[n][k] = *(const PG8_LAS bf16x8*)(lds + PG8_SB(b, h) + boff + n * 2048 + k * 1024); } while (0)
; #define PG8_MMA(ai, bj, At, Bt) do { __builtin_amdgcn_s_setprio(1); _Pragma("unroll") for (int m = 0; m < 4; ++m) _Pragma("unroll") for (int n = 0; n < 2; ++n) _Pragma("unroll") for (int k = 0; k < 2; ++k) \
;         acc[ai][bj][m][n] = __builtin_amdgcn_mfma_f32_16x16x32_bf16(Bt[n][k], At[m][k], acc[ai][bj][m][n], 0, 0, 0); __builtin_amdgcn_s_setprio(0); } while (0)
; #define PG8_WAIT_V(n) asm volatile("s_waitcnt vmcnt(" #n ")" ::: "memory")
; #define PG8_WAIT_L(n) asm volatile("s_waitcnt lgkmcnt(" #n ")" ::: "memory")
; #define PG8_BAR __builtin_amdgcn_s_barrier()
; #define PG8_SCHED __builtin_amdgcn_sched_barrier(0)
; template <class Epi, class Sched, bool ALIGN_EPI = false, bool SP2 = false>
; __device__ __forceinline__ void gemm_phase(PG8_LAS unsigned char* lds, const Gemm g, const Sched& S, const Epi& E) {
;     ...
;             const bool last = (t == nt - 2);
;             const char* a1 = cA + (size_t)(t + 1) * kstep;
;             const char* a2 = last ? nA : cA + (size_t)(t + 2) * kstep; const char* b2 = last ? nB : cB + (size_t)(t + 2) * kstep;
;             const char* a3 = a2 + kstep; const char* b3 = b2 + kstep;
;             if (last && has_next) S.a_ready(nxt);
;             if constexpr (SP2) {
;             PG8_LDB(B0, 0, 0); PG8_LDB(B1, 0, 1); PG8_SCHED; PG8_LDA(At, 0, 0); PG8_STAGE(PG8_SA(1, 1), a1 + hstep, voffA);
;             PG8_WAIT_V(8); PG8_WAIT_L(0); PG8_BAR; PG8_MMA(0, 0, At, B0); PG8_MMA(0, 1, At, B1); PG8_BAR; PG8_SCHED;
;             PG8_LDA(At, 0, 1); PG8_STAGE(PG8_SB(0, 0), b2, voffB); PG8_STAGE(PG8_SB(0, 1), b2 + hstepB, voffB); PG8_STAGE(PG8_SA(0, 0), a2, voffA);
.LBB0_586:
	ds_read_b128 v[166:169], v153
	ds_read_b128 v[170:173], v153 offset:1024
	ds_read_b128 v[174:177], v153 offset:2048
	ds_read_b128 v[178:181], v153 offset:3072
	ds_read_b128 v[182:185], v154
	ds_read_b128 v[186:189], v154 offset:1024
	ds_read_b128 v[190:193], v154 offset:2048
	ds_read_b128 v[194:197], v154 offset:3072
	s_add_u32 s28, s26, 0x4000
	s_addc_u32 s29, s27, 0
	s_cmp_eq_u32 s59, 12
	s_cselect_b32 s42, s55, s28
	s_cselect_b32 s43, s19, s29
	s_cselect_b32 s36, s56, s57
	s_cselect_b32 s37, s17, s58
	s_add_u32 s28, s42, 0x8000
	s_addc_u32 s29, s43, 0
	v_lshl_add_u64 v[232:233], s[26:27], 0, v[142:143]
	s_add_i32 m0, s3, 0xc000
	ds_read_b128 v[198:201], v155
	ds_read_b128 v[202:205], v155 offset:1024
	ds_read_b128 v[206:209], v155 offset:2048
	ds_read_b128 v[210:213], v155 offset:3072
	ds_read_b128 v[214:217], v155 offset:4096
	ds_read_b128 v[220:223], v155 offset:5120
	ds_read_b128 v[224:227], v155 offset:6144
	ds_read_b128 v[228:231], v155 offset:7168
	global_load_lds_dwordx4 v[232:233], off
	v_lshl_add_u64 v[232:233], s[26:27], 0, v[144:145]
	s_add_i32 m0, s3, 0xe000
	s_nop 0
	global_load_lds_dwordx4 v[232:233], off
	s_waitcnt vmcnt(8)
	s_waitcnt lgkmcnt(0)
	s_setprio 1
	s_barrier
	v_mfma_f32_16x16x32_bf16 v[126:129], v[166:169], v[198:201], v[126:129]
	v_mfma_f32_16x16x32_bf16 v[122:125], v[174:177], v[198:201], v[122:125]
	v_mfma_f32_16x16x32_bf16 v[110:113], v[166:169], v[206:209], v[110:113]
	v_mfma_f32_16x16x32_bf16 v[106:109], v[174:177], v[206:209], v[106:109]
	v_mfma_f32_16x16x32_bf16 v[94:97], v[166:169], v[214:217], v[94:97]
	v_mfma_f32_16x16x32_bf16 v[90:93], v[174:177], v[214:217], v[90:93]
	v_mfma_f32_16x16x32_bf16 v[78:81], v[166:169], v[224:227], v[78:81]
	v_mfma_f32_16x16x32_bf16 v[74:77], v[174:177], v[224:227], v[74:77]
	v_mfma_f32_16x16x32_bf16 v[126:129], v[170:173], v[202:205], v[126:129]
	v_mfma_f32_16x16x32_bf16 v[122:125], v[178:181], v[202:205], v[122:125]
	v_mfma_f32_16x16x32_bf16 v[110:113], v[170:173], v[210:213], v[110:113]
	v_mfma_f32_16x16x32_bf16 v[106:109], v[178:181], v[210:213], v[106:109]
	v_mfma_f32_16x16x32_bf16 v[94:97], v[170:173], v[220:223], v[94:97]
	v_mfma_f32_16x16x32_bf16 v[90:93], v[178:181], v[220:223], v[90:93]
	v_mfma_f32_16x16x32_bf16 v[78:81], v[170:173], v[228:231], v[78:81]
	v_mfma_f32_16x16x32_bf16 v[74:77], v[178:181], v[228:231], v[74:77]
	s_setprio 0
	s_setprio 1
	v_mfma_f32_16x16x32_bf16 v[118:121], v[182:185], v[198:201], v[118:121]
	v_mfma_f32_16x16x32_bf16 v[114:117], v[190:193], v[198:201], v[114:117]
	v_mfma_f32_16x16x32_bf16 v[102:105], v[182:185], v[206:209], v[102:105]
	v_mfma_f32_16x16x32_bf16 v[98:101], v[190:193], v[206:209], v[98:101]
	v_mfma_f32_16x16x32_bf16 v[86:89], v[182:185], v[214:217], v[86:89]
	v_mfma_f32_16x16x32_bf16 v[82:85], v[190:193], v[214:217], v[82:85]
	v_mfma_f32_16x16x32_bf16 v[70:73], v[182:185], v[224:227], v[70:73]
	v_mfma_f32_16x16x32_bf16 v[66:69], v[190:193], v[224:227], v[66:69]
	v_mfma_f32_16x16x32_bf16 v[118:121], v[186:189], v[202:205], v[118:121]
	v_mfma_f32_16x16x32_bf16 v[114:117], v[194:197], v[202:205], v[114:117]
	s_barrier
	v_mfma_f32_16x16x32_bf16 v[102:105], v[186:189], v[210:213], v[102:105]
	v_mfma_f32_16x16x32_bf16 v[98:101], v[194:197], v[210:213], v[98:101]
	v_mfma_f32_16x16x32_bf16 v[86:89], v[186:189], v[220:223], v[86:89]
	v_mfma_f32_16x16x32_bf16 v[82:85], v[194:197], v[220:223], v[82:85]
	v_mfma_f32_16x16x32_bf16 v[70:73], v[186:189], v[228:231], v[70:73]
	v_mfma_f32_16x16x32_bf16 v[66:69], v[194:197], v[228:231], v[66:69]
	s_setprio 0
	s_add_i32 s66, s8, s1
	v_lshl_add_u64 v[232:233], s[36:37], 0, v[132:133]
	s_mov_b32 m0, s66
	ds_read_b128 v[198:201], v155 offset:16384
	ds_read_b128 v[202:205], v155 offset:17408
	ds_read_b128 v[206:209], v155 offset:18432
	ds_read_b128 v[210:213], v155 offset:19456
	ds_read_b128 v[214:217], v155 offset:20480
	ds_read_b128 v[220:223], v155 offset:21504
	ds_read_b128 v[224:227], v155 offset:22528
	ds_read_b128 v[228:231], v155 offset:23552
	global_load_lds_dwordx4 v[232:233], off
	s_add_i32 m0, s66, 0x2000
	s_add_u32 s66, s36, 0x1000
	v_lshl_add_u64 v[232:233], s[36:37], 0, v[136:137]
	s_addc_u32 s67, s37, 0
	s_add_i32 s68, s52, s1
	global_load_lds_dwordx4 v[232:233], off
	v_lshl_add_u64 v[232:233], s[66:67], 0, v[132:133]
	s_mov_b32 m0, s68
	s_nop 0
	global_load_lds_dwordx4 v[232:233], off
	v_lshl_add_u64 v[232:233], s[66:67], 0, v[136:137]
	s_add_i32 m0, s68, 0x2000
	s_nop 0
	global_load_lds_dwordx4 v[232:233], off
	v_lshl_add_u64 v[232:233], s[42:43], 0, v[130:131]
	s_mov_b32 m0, s3
	s_nop 0
	global_load_lds_dwordx4 v[232:233], off
	v_lshl_add_u64 v[232:233], s[42:43], 0, v[134:135]
	s_mov_b32 m0, s44
	s_nop 0
	global_load_lds_dwordx4 v[232:233], off
	s_waitcnt vmcnt(8)
	s_waitcnt lgkmcnt(0)
	s_setprio 1
	s_barrier
; #define PG8_STAGE(bufoff, gbase, voff) do { _Pragma("unroll") for (int _i = 0; _i < 2; ++_i) \
;         __builtin_amdgcn_global_load_lds((const unsigned*)((const char*)(gbase) + (voff)[_i]), (PG8_LAS unsigned*)(lds + (bufoff) + ldsw + _i * 8192), 16, 0, 0); } while (0)
; #define PG8_LDA(dst, b, h) do { _Pragma("unroll") for (int m = 0; m < 4; ++m) _Pragma("unroll") for (int k = 0; k < 2; ++k) dst[m][k] = *(const PG8_LAS bf16x8*)(lds + PG8_SA(b, h) + aoff + m * 2048 + k * 1024); } while (0)
; #define PG8_LDB(dst, b, h) do { _Pragma("unroll") for (int n = 0; n < 2; ++n) _Pragma("unroll") for (int k = 0; k < 2; ++k) dst[n][k] = *(const PG8_LAS bf16x8*)(lds + PG8_SB(b, h) + boff + n * 2048 + k * 1024); } while (0)
; #define PG8_MMA(ai, bj, At, Bt) do { __builtin_amdgcn_s_setprio(1); _Pragma("unroll") for (int m = 0; m < 4; ++m) _Pragma("unroll") for (int n = 0; n < 2; ++n) _Pragma("unroll") for (int k = 0; k < 2; ++k) \
;         acc[ai][bj][m][n] = __builtin_amdgcn_mfma_f32_16x16x32_bf16(Bt[n][k], At[m][k], acc[ai][bj][m][n], 0, 0, 0); __builtin_amdgcn_s_setprio(0); } while (0)
; #define PG8_WAIT_V(n) asm volatile("s_waitcnt vmcnt(" #n ")" ::: "memory")
; #define PG8_WAIT_L(n) asm volatile("s_waitcnt lgkmcnt(" #n ")" ::: "memory")
; #define PG8_BAR __builtin_amdgcn_s_barrier()
; #define PG8_SCHED __builtin_amdgcn_sched_barrier(0)
; template <class Epi, class Sched, bool ALIGN_EPI = false, bool SP2 = false>
; __device__ __forceinline__ void gemm_phase(PG8_LAS unsigned char* lds, const Gemm g, const Sched& S, const Epi& E) {
;     ...
;             PG8_LDA(At, 0, 1); PG8_STAGE(PG8_SB(0, 0), b2, voffB); PG8_STAGE(PG8_SB(0, 1), b2 + hstepB, voffB); PG8_STAGE(PG8_SA(0, 0), a2, voffA);
;             PG8_WAIT_V(8); PG8_WAIT_L(0); PG8_BAR; PG8_MMA(1, 0, At, B0); PG8_MMA(1, 1, At, B1); PG8_BAR; PG8_SCHED;
;             PG8_LDB(B0, 1, 0); PG8_LDB(B1, 1, 1); PG8_SCHED; PG8_LDA(At, 1, 0); PG8_STAGE(PG8_SA(0, 1), a2 + hstep, voffA);
;             PG8_WAIT_V(8); PG8_WAIT_L(0); PG8_BAR; PG8_MMA(0, 0, At, B0); PG8_MMA(0, 1, At, B1); PG8_BAR; PG8_SCHED;
	v_mfma_f32_16x16x32_bf16 v[62:65], v[166:169], v[198:201], v[62:65]
	v_mfma_f32_16x16x32_bf16 v[58:61], v[174:177], v[198:201], v[58:61]
	v_mfma_f32_16x16x32_bf16 v[46:49], v[166:169], v[206:209], v[46:49]
	v_mfma_f32_16x16x32_bf16 v[42:45], v[174:177], v[206:209], v[42:45]
	v_mfma_f32_16x16x32_bf16 v[30:33], v[166:169], v[214:217], v[30:33]
	v_mfma_f32_16x16x32_bf16 v[26:29], v[174:177], v[214:217], v[26:29]
	v_mfma_f32_16x16x32_bf16 v[14:17], v[166:169], v[224:227], v[14:17]
	v_mfma_f32_16x16x32_bf16 v[10:13], v[174:177], v[224:227], v[10:13]
	v_mfma_f32_16x16x32_bf16 v[62:65], v[170:173], v[202:205], v[62:65]
	v_mfma_f32_16x16x32_bf16 v[58:61], v[178:181], v[202:205], v[58:61]
	v_mfma_f32_16x16x32_bf16 v[46:49], v[170:173], v[210:213], v[46:49]
	v_mfma_f32_16x16x32_bf16 v[42:45], v[178:181], v[210:213], v[42:45]
	v_mfma_f32_16x16x32_bf16 v[30:33], v[170:173], v[220:223], v[30:33]
	v_mfma_f32_16x16x32_bf16 v[26:29], v[178:181], v[220:223], v[26:29]
	v_mfma_f32_16x16x32_bf16 v[14:17], v[170:173], v[228:231], v[14:17]
	v_mfma_f32_16x16x32_bf16 v[10:13], v[178:181], v[228:231], v[10:13]
	s_setprio 0
	s_setprio 1
	v_mfma_f32_16x16x32_bf16 v[54:57], v[182:185], v[198:201], v[54:57]
	v_mfma_f32_16x16x32_bf16 v[50:53], v[190:193], v[198:201], v[50:53]
	v_mfma_f32_16x16x32_bf16 v[38:41], v[182:185], v[206:209], v[38:41]
	v_mfma_f32_16x16x32_bf16 v[34:37], v[190:193], v[206:209], v[34:37]
	v_mfma_f32_16x16x32_bf16 v[22:25], v[182:185], v[214:217], v[22:25]
	v_mfma_f32_16x16x32_bf16 v[18:21], v[190:193], v[214:217], v[18:21]
	v_mfma_f32_16x16x32_bf16 v[6:9], v[182:185], v[224:227], v[6:9]
	v_mfma_f32_16x16x32_bf16 v[2:5], v[190:193], v[224:227], v[2:5]
	v_mfma_f32_16x16x32_bf16 v[54:57], v[186:189], v[202:205], v[54:57]
	v_mfma_f32_16x16x32_bf16 v[50:53], v[194:197], v[202:205], v[50:53]
	s_barrier
	v_mfma_f32_16x16x32_bf16 v[38:41], v[186:189], v[210:213], v[38:41]
	v_mfma_f32_16x16x32_bf16 v[34:37], v[194:197], v[210:213], v[34:37]
	v_mfma_f32_16x16x32_bf16 v[22:25], v[186:189], v[220:223], v[22:25]
	v_mfma_f32_16x16x32_bf16 v[18:21], v[194:197], v[220:223], v[18:21]
	v_mfma_f32_16x16x32_bf16 v[6:9], v[186:189], v[228:231], v[6:9]
	v_mfma_f32_16x16x32_bf16 v[2:5], v[194:197], v[228:231], v[2:5]
	s_setprio 0
	s_add_i32 s66, 0, 0x18000
	v_add_u32_e32 v165, s66, v151
	s_add_i32 s67, 0, 0x1c000
	ds_read_b128 v[166:169], v165
	ds_read_b128 v[170:173], v165 offset:1024
	ds_read_b128 v[174:177], v165 offset:2048
	ds_read_b128 v[178:181], v165 offset:3072
	v_add_u32_e32 v165, s67, v151
	ds_read_b128 v[182:185], v165
	ds_read_b128 v[186:189], v165 offset:1024
	ds_read_b128 v[190:193], v165 offset:2048
	ds_read_b128 v[194:197], v165 offset:3072
	s_add_u32 s42, s42, 0x4000
	s_addc_u32 s43, s43, 0
	s_mov_b32 m0, s45
	v_lshl_add_u64 v[232:233], s[42:43], 0, v[130:131]
	ds_read_b128 v[198:201], v155 offset:32768
	ds_read_b128 v[202:205], v155 offset:33792
	ds_read_b128 v[206:209], v155 offset:34816
	ds_read_b128 v[210:213], v155 offset:35840
	ds_read_b128 v[214:217], v155 offset:36864
	ds_read_b128 v[220:223], v155 offset:37888
	ds_read_b128 v[224:227], v155 offset:38912
	ds_read_b128 v[228:231], v155 offset:39936
	global_load_lds_dwordx4 v[232:233], off
	v_lshl_add_u64 v[232:233], s[42:43], 0, v[134:135]
	s_mov_b32 m0, s46
	s_nop 0
	global_load_lds_dwordx4 v[232:233], off
	s_waitcnt vmcnt(8)
	s_waitcnt lgkmcnt(0)
	s_setprio 1
	s_barrier
	v_mfma_f32_16x16x32_bf16 v[126:129], v[166:169], v[198:201], v[126:129]
	v_mfma_f32_16x16x32_bf16 v[122:125], v[174:177], v[198:201], v[122:125]
	v_mfma_f32_16x16x32_bf16 v[110:113], v[166:169], v[206:209], v[110:113]
	v_mfma_f32_16x16x32_bf16 v[106:109], v[174:177], v[206:209], v[106:109]
	v_mfma_f32_16x16x32_bf16 v[94:97], v[166:169], v[214:217], v[94:97]
	v_mfma_f32_16x16x32_bf16 v[90:93], v[174:177], v[214:217], v[90:93]
	v_mfma_f32_16x16x32_bf16 v[78:81], v[166:169], v[224:227], v[78:81]
	v_mfma_f32_16x16x32_bf16 v[74:77], v[174:177], v[224:227], v[74:77]
	v_mfma_f32_16x16x32_bf16 v[126:129], v[170:173], v[202:205], v[126:129]
	v_mfma_f32_16x16x32_bf16 v[122:125], v[178:181], v[202:205], v[122:125]
	v_mfma_f32_16x16x32_bf16 v[110:113], v[170:173], v[210:213], v[110:113]
	v_mfma_f32_16x16x32_bf16 v[106:109], v[178:181], v[210:213], v[106:109]
	v_mfma_f32_16x16x32_bf16 v[94:97], v[170:173], v[220:223], v[94:97]
	v_mfma_f32_16x16x32_bf16 v[90:93], v[178:181], v[220:223], v[90:93]
	v_mfma_f32_16x16x32_bf16 v[78:81], v[170:173], v[228:231], v[78:81]
	v_mfma_f32_16x16x32_bf16 v[74:77], v[178:181], v[228:231], v[74:77]
	s_setprio 0
	s_setprio 1
	v_mfma_f32_16x16x32_bf16 v[118:121], v[182:185], v[198:201], v[118:121]
	v_mfma_f32_16x16x32_bf16 v[114:117], v[190:193], v[198:201], v[114:117]
	v_mfma_f32_16x16x32_bf16 v[102:105], v[182:185], v[206:209], v[102:105]
	v_mfma_f32_16x16x32_bf16 v[98:101], v[190:193], v[206:209], v[98:101]
	v_mfma_f32_16x16x32_bf16 v[86:89], v[182:185], v[214:217], v[86:89]
	v_mfma_f32_16x16x32_bf16 v[82:85], v[190:193], v[214:217], v[82:85]
	v_mfma_f32_16x16x32_bf16 v[70:73], v[182:185], v[224:227], v[70:73]
	v_mfma_f32_16x16x32_bf16 v[66:69], v[190:193], v[224:227], v[66:69]
	v_mfma_f32_16x16x32_bf16 v[118:121], v[186:189], v[202:205], v[118:121]
	v_mfma_f32_16x16x32_bf16 v[114:117], v[194:197], v[202:205], v[114:117]
	s_barrier
; #define PG8_STAGE(bufoff, gbase, voff) do { _Pragma("unroll") for (int _i = 0; _i < 2; ++_i) \
;         __builtin_amdgcn_global_load_lds((const unsigned*)((const char*)(gbase) + (voff)[_i]), (PG8_LAS unsigned*)(lds + (bufoff) + ldsw + _i * 8192), 16, 0, 0); } while (0)
; #define PG8_LDA(dst, b, h) do { _Pragma("unroll") for (int m = 0; m < 4; ++m) _Pragma("unroll") for (int k = 0; k < 2; ++k) dst[m][k] = *(const PG8_LAS bf16x8*)(lds + PG8_SA(b, h) + aoff + m * 2048 + k * 1024); } while (0)
; #define PG8_MMA(ai, bj, At, Bt) do { __builtin_amdgcn_s_setprio(1); _Pragma("unroll") for (int m = 0; m < 4; ++m) _Pragma("unroll") for (int n = 0; n < 2; ++n) _Pragma("unroll") for (int k = 0; k < 2; ++k) \
;         acc[ai][bj][m][n] = __builtin_amdgcn_mfma_f32_16x16x32_bf16(Bt[n][k], At[m][k], acc[ai][bj][m][n], 0, 0, 0); __builtin_amdgcn_s_setprio(0); } while (0)
; #define PG8_WAIT_V(n) asm volatile("s_waitcnt vmcnt(" #n ")" ::: "memory")
; #define PG8_WAIT_L(n) asm volatile("s_waitcnt lgkmcnt(" #n ")" ::: "memory")
; #define PG8_BAR __builtin_amdgcn_s_barrier()
; #define PG8_SCHED __builtin_amdgcn_sched_barrier(0)
; template <class Epi, class Sched, bool ALIGN_EPI = false, bool SP2 = false>
; __device__ __forceinline__ void gemm_phase(PG8_LAS unsigned char* lds, const Gemm g, const Sched& S, const Epi& E) {
;     ...
;             PG8_WAIT_V(8); PG8_WAIT_L(0); PG8_BAR; PG8_MMA(0, 0, At, B0); PG8_MMA(0, 1, At, B1); PG8_BAR; PG8_SCHED;
;             PG8_LDA(At, 1, 1); PG8_STAGE(PG8_SB(1, 0), b3, voffB); PG8_STAGE(PG8_SB(1, 1), b3 + hstepB, voffB); PG8_STAGE(PG8_SA(1, 0), a3, voffA);
;             PG8_WAIT_V(8); PG8_WAIT_L(0); PG8_BAR; PG8_MMA(1, 0, At, B0); PG8_MMA(1, 1, At, B1); PG8_BAR; PG8_SCHED;
;     ...
;         if constexpr (ALIGN_EPI) { if (wr == 0) PG8_BAR; }
	v_mfma_f32_16x16x32_bf16 v[102:105], v[186:189], v[210:213], v[102:105]
	v_mfma_f32_16x16x32_bf16 v[98:101], v[194:197], v[210:213], v[98:101]
	v_mfma_f32_16x16x32_bf16 v[86:89], v[186:189], v[220:223], v[86:89]
	v_mfma_f32_16x16x32_bf16 v[82:85], v[194:197], v[220:223], v[82:85]
	v_mfma_f32_16x16x32_bf16 v[70:73], v[186:189], v[228:231], v[70:73]
	v_mfma_f32_16x16x32_bf16 v[66:69], v[194:197], v[228:231], v[66:69]
	s_setprio 0
	s_add_u32 s42, s36, 0x8000
	s_addc_u32 s43, s37, 0
	s_add_i32 s66, s66, s1
	v_lshl_add_u64 v[232:233], s[42:43], 0, v[132:133]
	s_mov_b32 m0, s66
	ds_read_b128 v[198:201], v155 offset:49152
	ds_read_b128 v[202:205], v155 offset:50176
	ds_read_b128 v[206:209], v155 offset:51200
	ds_read_b128 v[210:213], v155 offset:52224
	ds_read_b128 v[214:217], v155 offset:53248
	ds_read_b128 v[220:223], v155 offset:54272
	ds_read_b128 v[224:227], v155 offset:55296
	ds_read_b128 v[228:231], v155 offset:56320
	global_load_lds_dwordx4 v[232:233], off
	s_add_i32 m0, s66, 0x2000
	s_add_u32 s36, s36, 0x9000
	v_lshl_add_u64 v[232:233], s[42:43], 0, v[136:137]
	s_addc_u32 s37, s37, 0
	s_add_i32 s42, s67, s1
	global_load_lds_dwordx4 v[232:233], off
	v_lshl_add_u64 v[232:233], s[36:37], 0, v[132:133]
	s_mov_b32 m0, s42
	s_nop 0
	global_load_lds_dwordx4 v[232:233], off
	v_lshl_add_u64 v[232:233], s[36:37], 0, v[136:137]
	s_add_i32 m0, s42, 0x2000
	s_nop 0
	global_load_lds_dwordx4 v[232:233], off
	v_lshl_add_u64 v[232:233], s[28:29], 0, v[130:131]
	s_mov_b32 m0, s49
	s_nop 0
	global_load_lds_dwordx4 v[232:233], off
	v_lshl_add_u64 v[232:233], s[28:29], 0, v[134:135]
	s_mov_b32 m0, s50
	s_nop 0
	global_load_lds_dwordx4 v[232:233], off
	s_waitcnt vmcnt(8)
	s_waitcnt lgkmcnt(0)
	s_setprio 1
	s_barrier
	v_mfma_f32_16x16x32_bf16 v[62:65], v[166:169], v[198:201], v[62:65]
	v_mfma_f32_16x16x32_bf16 v[58:61], v[174:177], v[198:201], v[58:61]
	v_mfma_f32_16x16x32_bf16 v[46:49], v[166:169], v[206:209], v[46:49]
	v_mfma_f32_16x16x32_bf16 v[42:45], v[174:177], v[206:209], v[42:45]
	v_mfma_f32_16x16x32_bf16 v[30:33], v[166:169], v[214:217], v[30:33]
	v_mfma_f32_16x16x32_bf16 v[26:29], v[174:177], v[214:217], v[26:29]
	v_mfma_f32_16x16x32_bf16 v[14:17], v[166:169], v[224:227], v[14:17]
	v_mfma_f32_16x16x32_bf16 v[10:13], v[174:177], v[224:227], v[10:13]
	v_mfma_f32_16x16x32_bf16 v[62:65], v[170:173], v[202:205], v[62:65]
	v_mfma_f32_16x16x32_bf16 v[58:61], v[178:181], v[202:205], v[58:61]
	v_mfma_f32_16x16x32_bf16 v[46:49], v[170:173], v[210:213], v[46:49]
	v_mfma_f32_16x16x32_bf16 v[42:45], v[178:181], v[210:213], v[42:45]
	v_mfma_f32_16x16x32_bf16 v[30:33], v[170:173], v[220:223], v[30:33]
	v_mfma_f32_16x16x32_bf16 v[26:29], v[178:181], v[220:223], v[26:29]
	v_mfma_f32_16x16x32_bf16 v[14:17], v[170:173], v[228:231], v[14:17]
	v_mfma_f32_16x16x32_bf16 v[10:13], v[178:181], v[228:231], v[10:13]
	s_setprio 0
	s_setprio 1
	v_mfma_f32_16x16x32_bf16 v[54:57], v[182:185], v[198:201], v[54:57]
	v_mfma_f32_16x16x32_bf16 v[50:53], v[190:193], v[198:201], v[50:53]
	v_mfma_f32_16x16x32_bf16 v[38:41], v[182:185], v[206:209], v[38:41]
	v_mfma_f32_16x16x32_bf16 v[34:37], v[190:193], v[206:209], v[34:37]
	v_mfma_f32_16x16x32_bf16 v[22:25], v[182:185], v[214:217], v[22:25]
	v_mfma_f32_16x16x32_bf16 v[18:21], v[190:193], v[214:217], v[18:21]
	v_mfma_f32_16x16x32_bf16 v[6:9], v[182:185], v[224:227], v[6:9]
	v_mfma_f32_16x16x32_bf16 v[2:5], v[190:193], v[224:227], v[2:5]
	v_mfma_f32_16x16x32_bf16 v[54:57], v[186:189], v[202:205], v[54:57]
	v_mfma_f32_16x16x32_bf16 v[50:53], v[194:197], v[202:205], v[50:53]
	s_barrier
	v_mfma_f32_16x16x32_bf16 v[38:41], v[186:189], v[210:213], v[38:41]
	v_mfma_f32_16x16x32_bf16 v[34:37], v[194:197], v[210:213], v[34:37]
	v_mfma_f32_16x16x32_bf16 v[22:25], v[186:189], v[220:223], v[22:25]
	v_mfma_f32_16x16x32_bf16 v[18:21], v[194:197], v[220:223], v[18:21]
	v_mfma_f32_16x16x32_bf16 v[6:9], v[186:189], v[228:231], v[6:9]
	v_mfma_f32_16x16x32_bf16 v[2:5], v[194:197], v[228:231], v[2:5]
	s_setprio 0
	s_add_i32 s59, s59, 2
	s_add_u32 s26, s26, 0x10000
	s_addc_u32 s27, s27, 0
	s_add_u32 s57, s57, 0x10000
	s_addc_u32 s58, s58, 0
	s_cmp_gt_u32 s59, 13
	s_cbranch_scc0 .LBB0_586
	s_and_b64 vcc, exec, s[12:13]
	s_cbranch_vccz .LBB0_589
	s_barrier

; #define PG8_STAGE(bufoff, gbase, voff) do { _Pragma("unroll") for (int _i = 0; _i < 2; ++_i) \
;         __builtin_amdgcn_global_load_lds((const unsigned*)((const char*)(gbase) + (voff)[_i]), (PG8_LAS unsigned*)(lds + (bufoff) + ldsw + _i * 8192), 16, 0, 0); } while (0)
; #define PG8_LDA(dst, b, h) do { _Pragma("unroll") for (int m = 0; m < 4; ++m) _Pragma("unroll") for (int k = 0; k < 2; ++k) dst[m][k] = *(const PG8_LAS bf16x8*)(lds + PG8_SA(b, h) + aoff + m * 2048 + k * 1024); } while (0)
; #define PG8_LDB(dst, b, h) do { _Pragma("unroll") for (int n = 0; n < 2; ++n) _Pragma("unroll") for (int k = 0; k < 2; ++k) dst[n][k] = *(const PG8_LAS bf16x8*)(lds + PG8_SB(b, h) + boff + n * 2048 + k * 1024); } while (0)
; #define PG8_MMA(ai, bj, At, Bt) do { __builtin_amdgcn_s_setprio(1); _Pragma("unroll") for (int m = 0; m < 4; ++m) _Pragma("unroll") for (int n = 0; n < 2; ++n) _Pragma("unroll") for (int k = 0; k < 2; ++k) \
;         acc[ai][bj][m][n] = __builtin_amdgcn_mfma_f32_16x16x32_bf16(Bt[n][k], At[m][k], acc[ai][bj][m][n], 0, 0, 0); __builtin_amdgcn_s_setprio(0); } while (0)
; #define PG8_WAIT_V(n) asm volatile("s_waitcnt vmcnt(" #n ")" ::: "memory")
; #define PG8_WAIT_L(n) asm volatile("s_waitcnt lgkmcnt(" #n ")" ::: "memory")
; #define PG8_BAR __builtin_amdgcn_s_barrier()
; #define PG8_SCHED __builtin_amdgcn_sched_barrier(0)
; template <class Epi, class Sched, bool ALIGN_EPI = false, bool SP2 = false>
; __device__ __forceinline__ void gemm_phase(PG8_LAS unsigned char* lds, const Gemm g, const Sched& S, const Epi& E) {
;     ...
;             const bool last = (t == nt - 2);
;             const char* a1 = cA + (size_t)(t + 1) * kstep;
;             const char* a2 = last ? nA : cA + (size_t)(t + 2) * kstep; const char* b2 = last ? nB : cB + (size_t)(t + 2) * kstep;
;             const char* a3 = a2 + kstep; const char* b3 = b2 + kstep;
;             if (last && has_next) S.a_ready(nxt);
;             if constexpr (SP2) {
;             PG8_LDB(B0, 0, 0); PG8_LDB(B1, 0, 1); PG8_SCHED; PG8_LDA(At, 0, 0); PG8_STAGE(PG8_SA(1, 1), a1 + hstep, voffA);
;             PG8_WAIT_V(8); PG8_WAIT_L(0); PG8_BAR; PG8_MMA(0, 0, At, B0); PG8_MMA(0, 1, At, B1); PG8_BAR; PG8_SCHED;
;             PG8_LDA(At, 0, 1); PG8_STAGE(PG8_SB(0, 0), b2, voffB); PG8_STAGE(PG8_SB(0, 1), b2 + hstepB, voffB); PG8_STAGE(PG8_SA(0, 0), a2, voffA);
.LBB0_682:
	ds_read_b128 v[98:101], v215
	ds_read_b128 v[102:105], v215 offset:1024
	ds_read_b128 v[122:125], v215 offset:2048
	ds_read_b128 v[126:129], v215 offset:3072
	ds_read_b128 v[146:149], v216
	ds_read_b128 v[150:153], v216 offset:1024
	ds_read_b128 v[154:157], v216 offset:2048
	ds_read_b128 v[158:161], v216 offset:3072
	s_add_u32 s42, s36, 0x4000
	s_addc_u32 s43, s37, 0
	s_cmp_eq_u32 s54, 60
	s_cselect_b32 s46, s23, s42
	s_cselect_b32 s47, s9, s43
	s_cselect_b32 s44, s29, s52
	s_cselect_b32 s45, s21, s53
	s_add_u32 s42, s46, 0x8000
	s_addc_u32 s43, s47, 0
	v_lshl_add_u64 v[230:231], s[36:37], 0, v[198:199]
	s_add_i32 m0, s1, 0xc000
	ds_read_b128 v[162:165], v217
	ds_read_b128 v[166:169], v217 offset:1024
	ds_read_b128 v[170:173], v217 offset:2048
	ds_read_b128 v[174:177], v217 offset:3072
	ds_read_b128 v[178:181], v217 offset:4096
	ds_read_b128 v[182:185], v217 offset:5120
	ds_read_b128 v[222:225], v217 offset:6144
	ds_read_b128 v[226:229], v217 offset:7168
	global_load_lds_dwordx4 v[230:231], off
	v_lshl_add_u64 v[230:231], s[36:37], 0, v[200:201]
	s_add_i32 m0, s1, 0xe000
	s_nop 0
	global_load_lds_dwordx4 v[230:231], off
	s_waitcnt vmcnt(8)
	s_waitcnt lgkmcnt(0)
	s_setprio 1
	s_barrier
	v_mfma_f32_16x16x32_bf16 v[142:145], v[98:101], v[162:165], v[142:145]
	v_mfma_f32_16x16x32_bf16 v[138:141], v[122:125], v[162:165], v[138:141]
	v_mfma_f32_16x16x32_bf16 v[118:121], v[98:101], v[170:173], v[118:121]
	v_mfma_f32_16x16x32_bf16 v[114:117], v[122:125], v[170:173], v[114:117]
	v_mfma_f32_16x16x32_bf16 v[94:97], v[98:101], v[178:181], v[94:97]
	v_mfma_f32_16x16x32_bf16 v[90:93], v[122:125], v[178:181], v[90:93]
	v_mfma_f32_16x16x32_bf16 v[78:81], v[98:101], v[222:225], v[78:81]
	v_mfma_f32_16x16x32_bf16 v[74:77], v[122:125], v[222:225], v[74:77]
	v_mfma_f32_16x16x32_bf16 v[142:145], v[102:105], v[166:169], v[142:145]
	v_mfma_f32_16x16x32_bf16 v[138:141], v[126:129], v[166:169], v[138:141]
	v_mfma_f32_16x16x32_bf16 v[118:121], v[102:105], v[174:177], v[118:121]
	v_mfma_f32_16x16x32_bf16 v[114:117], v[126:129], v[174:177], v[114:117]
	v_mfma_f32_16x16x32_bf16 v[94:97], v[102:105], v[182:185], v[94:97]
	v_mfma_f32_16x16x32_bf16 v[90:93], v[126:129], v[182:185], v[90:93]
	v_mfma_f32_16x16x32_bf16 v[78:81], v[102:105], v[226:229], v[78:81]
	v_mfma_f32_16x16x32_bf16 v[74:77], v[126:129], v[226:229], v[74:77]
	s_setprio 0
	s_setprio 1
	v_mfma_f32_16x16x32_bf16 v[134:137], v[146:149], v[162:165], v[134:137]
	v_mfma_f32_16x16x32_bf16 v[130:133], v[154:157], v[162:165], v[130:133]
	v_mfma_f32_16x16x32_bf16 v[110:113], v[146:149], v[170:173], v[110:113]
	v_mfma_f32_16x16x32_bf16 v[106:109], v[154:157], v[170:173], v[106:109]
	v_mfma_f32_16x16x32_bf16 v[86:89], v[146:149], v[178:181], v[86:89]
	v_mfma_f32_16x16x32_bf16 v[82:85], v[154:157], v[178:181], v[82:85]
	v_mfma_f32_16x16x32_bf16 v[70:73], v[146:149], v[222:225], v[70:73]
	v_mfma_f32_16x16x32_bf16 v[66:69], v[154:157], v[222:225], v[66:69]
	v_mfma_f32_16x16x32_bf16 v[134:137], v[150:153], v[166:169], v[134:137]
	v_mfma_f32_16x16x32_bf16 v[130:133], v[158:161], v[166:169], v[130:133]
	s_barrier
	v_mfma_f32_16x16x32_bf16 v[110:113], v[150:153], v[174:177], v[110:113]
	v_mfma_f32_16x16x32_bf16 v[106:109], v[158:161], v[174:177], v[106:109]
	v_mfma_f32_16x16x32_bf16 v[86:89], v[150:153], v[182:185], v[86:89]
	v_mfma_f32_16x16x32_bf16 v[82:85], v[158:161], v[182:185], v[82:85]
	v_mfma_f32_16x16x32_bf16 v[70:73], v[150:153], v[226:229], v[70:73]
	v_mfma_f32_16x16x32_bf16 v[66:69], v[158:161], v[226:229], v[66:69]
	s_setprio 0
	s_add_i32 s55, s59, s0
	v_lshl_add_u64 v[230:231], s[44:45], 0, v[188:189]
	s_mov_b32 m0, s55
	ds_read_b128 v[162:165], v217 offset:16384
	ds_read_b128 v[166:169], v217 offset:17408
	ds_read_b128 v[170:173], v217 offset:18432
	ds_read_b128 v[174:177], v217 offset:19456
	ds_read_b128 v[178:181], v217 offset:20480
	ds_read_b128 v[182:185], v217 offset:21504
	ds_read_b128 v[222:225], v217 offset:22528
	ds_read_b128 v[226:229], v217 offset:23552
	global_load_lds_dwordx4 v[230:231], off
	s_add_i32 m0, s55, 0x2000
	s_add_u32 s68, s44, 0x1000
	v_lshl_add_u64 v[230:231], s[44:45], 0, v[192:193]
	s_addc_u32 s69, s45, 0
	s_add_i32 s55, s64, s0
	global_load_lds_dwordx4 v[230:231], off
	v_lshl_add_u64 v[230:231], s[68:69], 0, v[188:189]
	s_mov_b32 m0, s55
	s_nop 0
	global_load_lds_dwordx4 v[230:231], off
	v_lshl_add_u64 v[230:231], s[68:69], 0, v[192:193]
	s_add_i32 m0, s55, 0x2000
	s_nop 0
	global_load_lds_dwordx4 v[230:231], off
	v_lshl_add_u64 v[230:231], s[46:47], 0, v[186:187]
	s_mov_b32 m0, s1
	s_nop 0
	global_load_lds_dwordx4 v[230:231], off
	v_lshl_add_u64 v[230:231], s[46:47], 0, v[190:191]
	s_mov_b32 m0, s3
	s_nop 0
	global_load_lds_dwordx4 v[230:231], off
	s_waitcnt vmcnt(8)
	s_waitcnt lgkmcnt(0)
	s_setprio 1
	s_barrier
; #define PG8_STAGE(bufoff, gbase, voff) do { _Pragma("unroll") for (int _i = 0; _i < 2; ++_i) \
;         __builtin_amdgcn_global_load_lds((const unsigned*)((const char*)(gbase) + (voff)[_i]), (PG8_LAS unsigned*)(lds + (bufoff) + ldsw + _i * 8192), 16, 0, 0); } while (0)
; #define PG8_LDA(dst, b, h) do { _Pragma("unroll") for (int m = 0; m < 4; ++m) _Pragma("unroll") for (int k = 0; k < 2; ++k) dst[m][k] = *(const PG8_LAS bf16x8*)(lds + PG8_SA(b, h) + aoff + m * 2048 + k * 1024); } while (0)
; #define PG8_LDB(dst, b, h) do { _Pragma("unroll") for (int n = 0; n < 2; ++n) _Pragma("unroll") for (int k = 0; k < 2; ++k) dst[n][k] = *(const PG8_LAS bf16x8*)(lds + PG8_SB(b, h) + boff + n * 2048 + k * 1024); } while (0)
; #define PG8_MMA(ai, bj, At, Bt) do { __builtin_amdgcn_s_setprio(1); _Pragma("unroll") for (int m = 0; m < 4; ++m) _Pragma("unroll") for (int n = 0; n < 2; ++n) _Pragma("unroll") for (int k = 0; k < 2; ++k) \
;         acc[ai][bj][m][n] = __builtin_amdgcn_mfma_f32_16x16x32_bf16(Bt[n][k], At[m][k], acc[ai][bj][m][n], 0, 0, 0); __builtin_amdgcn_s_setprio(0); } while (0)
; #define PG8_WAIT_V(n) asm volatile("s_waitcnt vmcnt(" #n ")" ::: "memory")
; #define PG8_WAIT_L(n) asm volatile("s_waitcnt lgkmcnt(" #n ")" ::: "memory")
; #define PG8_BAR __builtin_amdgcn_s_barrier()
; #define PG8_SCHED __builtin_amdgcn_sched_barrier(0)
; template <class Epi, class Sched, bool ALIGN_EPI = false, bool SP2 = false>
; __device__ __forceinline__ void gemm_phase(PG8_LAS unsigned char* lds, const Gemm g, const Sched& S, const Epi& E) {
;     ...
;             PG8_LDA(At, 0, 1); PG8_STAGE(PG8_SB(0, 0), b2, voffB); PG8_STAGE(PG8_SB(0, 1), b2 + hstepB, voffB); PG8_STAGE(PG8_SA(0, 0), a2, voffA);
;             PG8_WAIT_V(8); PG8_WAIT_L(0); PG8_BAR; PG8_MMA(1, 0, At, B0); PG8_MMA(1, 1, At, B1); PG8_BAR; PG8_SCHED;
;             PG8_LDB(B0, 1, 0); PG8_LDB(B1, 1, 1); PG8_SCHED; PG8_LDA(At, 1, 0); PG8_STAGE(PG8_SA(0, 1), a2 + hstep, voffA);
;             PG8_WAIT_V(8); PG8_WAIT_L(0); PG8_BAR; PG8_MMA(0, 0, At, B0); PG8_MMA(0, 1, At, B1); PG8_BAR; PG8_SCHED;
	v_mfma_f32_16x16x32_bf16 v[62:65], v[98:101], v[162:165], v[62:65]
	v_mfma_f32_16x16x32_bf16 v[58:61], v[122:125], v[162:165], v[58:61]
	v_mfma_f32_16x16x32_bf16 v[46:49], v[98:101], v[170:173], v[46:49]
	v_mfma_f32_16x16x32_bf16 v[42:45], v[122:125], v[170:173], v[42:45]
	v_mfma_f32_16x16x32_bf16 v[30:33], v[98:101], v[178:181], v[30:33]
	v_mfma_f32_16x16x32_bf16 v[26:29], v[122:125], v[178:181], v[26:29]
	v_mfma_f32_16x16x32_bf16 v[14:17], v[98:101], v[222:225], v[14:17]
	v_mfma_f32_16x16x32_bf16 v[10:13], v[122:125], v[222:225], v[10:13]
	v_mfma_f32_16x16x32_bf16 v[62:65], v[102:105], v[166:169], v[62:65]
	v_mfma_f32_16x16x32_bf16 v[58:61], v[126:129], v[166:169], v[58:61]
	v_mfma_f32_16x16x32_bf16 v[46:49], v[102:105], v[174:177], v[46:49]
	v_mfma_f32_16x16x32_bf16 v[42:45], v[126:129], v[174:177], v[42:45]
	v_mfma_f32_16x16x32_bf16 v[30:33], v[102:105], v[182:185], v[30:33]
	v_mfma_f32_16x16x32_bf16 v[26:29], v[126:129], v[182:185], v[26:29]
	v_mfma_f32_16x16x32_bf16 v[14:17], v[102:105], v[226:229], v[14:17]
	v_mfma_f32_16x16x32_bf16 v[10:13], v[126:129], v[226:229], v[10:13]
	s_setprio 0
	s_setprio 1
	v_mfma_f32_16x16x32_bf16 v[54:57], v[146:149], v[162:165], v[54:57]
	v_mfma_f32_16x16x32_bf16 v[50:53], v[154:157], v[162:165], v[50:53]
	v_mfma_f32_16x16x32_bf16 v[38:41], v[146:149], v[170:173], v[38:41]
	v_mfma_f32_16x16x32_bf16 v[34:37], v[154:157], v[170:173], v[34:37]
	v_mfma_f32_16x16x32_bf16 v[22:25], v[146:149], v[178:181], v[22:25]
	v_mfma_f32_16x16x32_bf16 v[18:21], v[154:157], v[178:181], v[18:21]
	v_mfma_f32_16x16x32_bf16 v[6:9], v[146:149], v[222:225], v[6:9]
	v_mfma_f32_16x16x32_bf16 v[2:5], v[154:157], v[222:225], v[2:5]
	v_mfma_f32_16x16x32_bf16 v[54:57], v[150:153], v[166:169], v[54:57]
	v_mfma_f32_16x16x32_bf16 v[50:53], v[158:161], v[166:169], v[50:53]
	s_barrier
	v_mfma_f32_16x16x32_bf16 v[38:41], v[150:153], v[174:177], v[38:41]
	v_mfma_f32_16x16x32_bf16 v[34:37], v[158:161], v[174:177], v[34:37]
	v_mfma_f32_16x16x32_bf16 v[22:25], v[150:153], v[182:185], v[22:25]
	v_mfma_f32_16x16x32_bf16 v[18:21], v[158:161], v[182:185], v[18:21]
	v_mfma_f32_16x16x32_bf16 v[6:9], v[150:153], v[226:229], v[6:9]
	v_mfma_f32_16x16x32_bf16 v[2:5], v[158:161], v[226:229], v[2:5]
	s_setprio 0
	s_add_i32 s55, 0, 0x18000
	s_add_i32 s67, 0, 0x1c000
	v_add_u32_e32 v126, s55, v214
	v_add_u32_e32 v158, s67, v214
	ds_read_b128 v[98:101], v126
	ds_read_b128 v[102:105], v126 offset:1024
	ds_read_b128 v[122:125], v126 offset:2048
	ds_read_b128 v[126:129], v126 offset:3072
	ds_read_b128 v[146:149], v158
	ds_read_b128 v[150:153], v158 offset:1024
	ds_read_b128 v[154:157], v158 offset:2048
	ds_read_b128 v[158:161], v158 offset:3072
	s_add_u32 s46, s46, 0x4000
	s_addc_u32 s47, s47, 0
	s_mov_b32 m0, s48
	v_lshl_add_u64 v[230:231], s[46:47], 0, v[186:187]
	ds_read_b128 v[162:165], v217 offset:32768
	ds_read_b128 v[166:169], v217 offset:33792
	ds_read_b128 v[170:173], v217 offset:34816
	ds_read_b128 v[174:177], v217 offset:35840
	ds_read_b128 v[178:181], v217 offset:36864
	ds_read_b128 v[182:185], v217 offset:37888
	ds_read_b128 v[222:225], v217 offset:38912
	ds_read_b128 v[226:229], v217 offset:39936
	global_load_lds_dwordx4 v[230:231], off
	v_lshl_add_u64 v[230:231], s[46:47], 0, v[190:191]
	s_mov_b32 m0, s49
	s_nop 0
	global_load_lds_dwordx4 v[230:231], off
	s_waitcnt vmcnt(8)
	s_waitcnt lgkmcnt(0)
	s_setprio 1
	s_barrier
	v_mfma_f32_16x16x32_bf16 v[142:145], v[98:101], v[162:165], v[142:145]
	v_mfma_f32_16x16x32_bf16 v[138:141], v[122:125], v[162:165], v[138:141]
	v_mfma_f32_16x16x32_bf16 v[118:121], v[98:101], v[170:173], v[118:121]
	v_mfma_f32_16x16x32_bf16 v[114:117], v[122:125], v[170:173], v[114:117]
	v_mfma_f32_16x16x32_bf16 v[94:97], v[98:101], v[178:181], v[94:97]
	v_mfma_f32_16x16x32_bf16 v[90:93], v[122:125], v[178:181], v[90:93]
	v_mfma_f32_16x16x32_bf16 v[78:81], v[98:101], v[222:225], v[78:81]
	v_mfma_f32_16x16x32_bf16 v[74:77], v[122:125], v[222:225], v[74:77]
	v_mfma_f32_16x16x32_bf16 v[142:145], v[102:105], v[166:169], v[142:145]
	v_mfma_f32_16x16x32_bf16 v[138:141], v[126:129], v[166:169], v[138:141]
	v_mfma_f32_16x16x32_bf16 v[118:121], v[102:105], v[174:177], v[118:121]
	v_mfma_f32_16x16x32_bf16 v[114:117], v[126:129], v[174:177], v[114:117]
	v_mfma_f32_16x16x32_bf16 v[94:97], v[102:105], v[182:185], v[94:97]
	v_mfma_f32_16x16x32_bf16 v[90:93], v[126:129], v[182:185], v[90:93]
	v_mfma_f32_16x16x32_bf16 v[78:81], v[102:105], v[226:229], v[78:81]
	v_mfma_f32_16x16x32_bf16 v[74:77], v[126:129], v[226:229], v[74:77]
	s_setprio 0
	s_setprio 1
	v_mfma_f32_16x16x32_bf16 v[134:137], v[146:149], v[162:165], v[134:137]
	v_mfma_f32_16x16x32_bf16 v[130:133], v[154:157], v[162:165], v[130:133]
	v_mfma_f32_16x16x32_bf16 v[110:113], v[146:149], v[170:173], v[110:113]
	v_mfma_f32_16x16x32_bf16 v[106:109], v[154:157], v[170:173], v[106:109]
	v_mfma_f32_16x16x32_bf16 v[86:89], v[146:149], v[178:181], v[86:89]
	v_mfma_f32_16x16x32_bf16 v[82:85], v[154:157], v[178:181], v[82:85]
	v_mfma_f32_16x16x32_bf16 v[70:73], v[146:149], v[222:225], v[70:73]
	v_mfma_f32_16x16x32_bf16 v[66:69], v[154:157], v[222:225], v[66:69]
	v_mfma_f32_16x16x32_bf16 v[134:137], v[150:153], v[166:169], v[134:137]
	v_mfma_f32_16x16x32_bf16 v[130:133], v[158:161], v[166:169], v[130:133]
	s_barrier
; #define PG8_STAGE(bufoff, gbase, voff) do { _Pragma("unroll") for (int _i = 0; _i < 2; ++_i) \
;         __builtin_amdgcn_global_load_lds((const unsigned*)((const char*)(gbase) + (voff)[_i]), (PG8_LAS unsigned*)(lds + (bufoff) + ldsw + _i * 8192), 16, 0, 0); } while (0)
; #define PG8_LDA(dst, b, h) do { _Pragma("unroll") for (int m = 0; m < 4; ++m) _Pragma("unroll") for (int k = 0; k < 2; ++k) dst[m][k] = *(const PG8_LAS bf16x8*)(lds + PG8_SA(b, h) + aoff + m * 2048 + k * 1024); } while (0)
; #define PG8_MMA(ai, bj, At, Bt) do { __builtin_amdgcn_s_setprio(1); _Pragma("unroll") for (int m = 0; m < 4; ++m) _Pragma("unroll") for (int n = 0; n < 2; ++n) _Pragma("unroll") for (int k = 0; k < 2; ++k) \
;         acc[ai][bj][m][n] = __builtin_amdgcn_mfma_f32_16x16x32_bf16(Bt[n][k], At[m][k], acc[ai][bj][m][n], 0, 0, 0); __builtin_amdgcn_s_setprio(0); } while (0)
; #define PG8_WAIT_V(n) asm volatile("s_waitcnt vmcnt(" #n ")" ::: "memory")
; #define PG8_WAIT_L(n) asm volatile("s_waitcnt lgkmcnt(" #n ")" ::: "memory")
; #define PG8_BAR __builtin_amdgcn_s_barrier()
; #define PG8_SCHED __builtin_amdgcn_sched_barrier(0)
; template <class Epi, class Sched, bool ALIGN_EPI = false, bool SP2 = false>
; __device__ __forceinline__ void gemm_phase(PG8_LAS unsigned char* lds, const Gemm g, const Sched& S, const Epi& E) {
;     ...
;             PG8_WAIT_V(8); PG8_WAIT_L(0); PG8_BAR; PG8_MMA(0, 0, At, B0); PG8_MMA(0, 1, At, B1); PG8_BAR; PG8_SCHED;
;             PG8_LDA(At, 1, 1); PG8_STAGE(PG8_SB(1, 0), b3, voffB); PG8_STAGE(PG8_SB(1, 1), b3 + hstepB, voffB); PG8_STAGE(PG8_SA(1, 0), a3, voffA);
;             PG8_WAIT_V(8); PG8_WAIT_L(0); PG8_BAR; PG8_MMA(1, 0, At, B0); PG8_MMA(1, 1, At, B1); PG8_BAR; PG8_SCHED;
;     ...
;         if constexpr (ALIGN_EPI) { if (wr == 0) PG8_BAR; }
	v_mfma_f32_16x16x32_bf16 v[110:113], v[150:153], v[174:177], v[110:113]
	v_mfma_f32_16x16x32_bf16 v[106:109], v[158:161], v[174:177], v[106:109]
	v_mfma_f32_16x16x32_bf16 v[86:89], v[150:153], v[182:185], v[86:89]
	v_mfma_f32_16x16x32_bf16 v[82:85], v[158:161], v[182:185], v[82:85]
	v_mfma_f32_16x16x32_bf16 v[70:73], v[150:153], v[226:229], v[70:73]
	v_mfma_f32_16x16x32_bf16 v[66:69], v[158:161], v[226:229], v[66:69]
	s_setprio 0
	s_add_u32 s46, s44, 0x8000
	s_addc_u32 s47, s45, 0
	s_add_i32 s55, s55, s0
	v_lshl_add_u64 v[230:231], s[46:47], 0, v[188:189]
	s_mov_b32 m0, s55
	ds_read_b128 v[162:165], v217 offset:49152
	ds_read_b128 v[166:169], v217 offset:50176
	ds_read_b128 v[170:173], v217 offset:51200
	ds_read_b128 v[174:177], v217 offset:52224
	ds_read_b128 v[178:181], v217 offset:53248
	ds_read_b128 v[182:185], v217 offset:54272
	ds_read_b128 v[222:225], v217 offset:55296
	ds_read_b128 v[226:229], v217 offset:56320
	global_load_lds_dwordx4 v[230:231], off
	s_add_i32 m0, s55, 0x2000
	s_add_u32 s44, s44, 0x9000
	v_lshl_add_u64 v[230:231], s[46:47], 0, v[192:193]
	s_addc_u32 s45, s45, 0
	s_add_i32 s46, s67, s0
	global_load_lds_dwordx4 v[230:231], off
	v_lshl_add_u64 v[230:231], s[44:45], 0, v[188:189]
	s_mov_b32 m0, s46
	s_nop 0
	global_load_lds_dwordx4 v[230:231], off
	v_lshl_add_u64 v[230:231], s[44:45], 0, v[192:193]
	s_add_i32 m0, s46, 0x2000
	s_nop 0
	global_load_lds_dwordx4 v[230:231], off
	v_lshl_add_u64 v[230:231], s[42:43], 0, v[186:187]
	s_mov_b32 m0, s56
	s_nop 0
	global_load_lds_dwordx4 v[230:231], off
	v_lshl_add_u64 v[230:231], s[42:43], 0, v[190:191]
	s_mov_b32 m0, s57
	s_nop 0
	global_load_lds_dwordx4 v[230:231], off
	s_waitcnt vmcnt(8)
	s_waitcnt lgkmcnt(0)
	s_setprio 1
	s_barrier
	v_mfma_f32_16x16x32_bf16 v[62:65], v[98:101], v[162:165], v[62:65]
	v_mfma_f32_16x16x32_bf16 v[58:61], v[122:125], v[162:165], v[58:61]
	v_mfma_f32_16x16x32_bf16 v[46:49], v[98:101], v[170:173], v[46:49]
	v_mfma_f32_16x16x32_bf16 v[42:45], v[122:125], v[170:173], v[42:45]
	v_mfma_f32_16x16x32_bf16 v[30:33], v[98:101], v[178:181], v[30:33]
	v_mfma_f32_16x16x32_bf16 v[26:29], v[122:125], v[178:181], v[26:29]
	v_mfma_f32_16x16x32_bf16 v[14:17], v[98:101], v[222:225], v[14:17]
	v_mfma_f32_16x16x32_bf16 v[10:13], v[122:125], v[222:225], v[10:13]
	v_mfma_f32_16x16x32_bf16 v[62:65], v[102:105], v[166:169], v[62:65]
	v_mfma_f32_16x16x32_bf16 v[58:61], v[126:129], v[166:169], v[58:61]
	v_mfma_f32_16x16x32_bf16 v[46:49], v[102:105], v[174:177], v[46:49]
	v_mfma_f32_16x16x32_bf16 v[42:45], v[126:129], v[174:177], v[42:45]
	v_mfma_f32_16x16x32_bf16 v[30:33], v[102:105], v[182:185], v[30:33]
	v_mfma_f32_16x16x32_bf16 v[26:29], v[126:129], v[182:185], v[26:29]
	v_mfma_f32_16x16x32_bf16 v[14:17], v[102:105], v[226:229], v[14:17]
	v_mfma_f32_16x16x32_bf16 v[10:13], v[126:129], v[226:229], v[10:13]
	s_setprio 0
	s_setprio 1
	v_mfma_f32_16x16x32_bf16 v[54:57], v[146:149], v[162:165], v[54:57]
	v_mfma_f32_16x16x32_bf16 v[50:53], v[154:157], v[162:165], v[50:53]
	v_mfma_f32_16x16x32_bf16 v[38:41], v[146:149], v[170:173], v[38:41]
	v_mfma_f32_16x16x32_bf16 v[34:37], v[154:157], v[170:173], v[34:37]
	v_mfma_f32_16x16x32_bf16 v[22:25], v[146:149], v[178:181], v[22:25]
	v_mfma_f32_16x16x32_bf16 v[18:21], v[154:157], v[178:181], v[18:21]
	v_mfma_f32_16x16x32_bf16 v[6:9], v[146:149], v[222:225], v[6:9]
	v_mfma_f32_16x16x32_bf16 v[2:5], v[154:157], v[222:225], v[2:5]
	v_mfma_f32_16x16x32_bf16 v[54:57], v[150:153], v[166:169], v[54:57]
	v_mfma_f32_16x16x32_bf16 v[50:53], v[158:161], v[166:169], v[50:53]
	s_barrier
	v_mfma_f32_16x16x32_bf16 v[38:41], v[150:153], v[174:177], v[38:41]
	v_mfma_f32_16x16x32_bf16 v[34:37], v[158:161], v[174:177], v[34:37]
	v_mfma_f32_16x16x32_bf16 v[22:25], v[150:153], v[182:185], v[22:25]
	v_mfma_f32_16x16x32_bf16 v[18:21], v[158:161], v[182:185], v[18:21]
	v_mfma_f32_16x16x32_bf16 v[6:9], v[150:153], v[226:229], v[6:9]
	v_mfma_f32_16x16x32_bf16 v[2:5], v[158:161], v[226:229], v[2:5]
	s_setprio 0
	s_add_i32 s54, s54, 2
	s_add_u32 s36, s36, 0x10000
	s_addc_u32 s37, s37, 0
	s_add_u32 s52, s52, 0x10000
	s_addc_u32 s53, s53, 0
	s_cmp_gt_u32 s54, 61
	s_cbranch_scc0 .LBB0_682
	s_and_b64 vcc, exec, s[18:19]
	s_cbranch_vccz .LBB0_685
	s_barrier

; #define PG8_STAGE(bufoff, gbase, voff) do { _Pragma("unroll") for (int _i = 0; _i < 2; ++_i) \
;         __builtin_amdgcn_global_load_lds((const unsigned*)((const char*)(gbase) + (voff)[_i]), (PG8_LAS unsigned*)(lds + (bufoff) + ldsw + _i * 8192), 16, 0, 0); } while (0)
; #define PG8_LDA(dst, b, h) do { _Pragma("unroll") for (int m = 0; m < 4; ++m) _Pragma("unroll") for (int k = 0; k < 2; ++k) dst[m][k] = *(const PG8_LAS bf16x8*)(lds + PG8_SA(b, h) + aoff + m * 2048 + k * 1024); } while (0)
; #define PG8_LDB(dst, b, h) do { _Pragma("unroll") for (int n = 0; n < 2; ++n) _Pragma("unroll") for (int k = 0; k < 2; ++k) dst[n][k] = *(const PG8_LAS bf16x8*)(lds + PG8_SB(b, h) + boff + n * 2048 + k * 1024); } while (0)
; #define PG8_MMA(ai, bj, At, Bt) do { __builtin_amdgcn_s_setprio(1); _Pragma("unroll") for (int m = 0; m < 4; ++m) _Pragma("unroll") for (int n = 0; n < 2; ++n) _Pragma("unroll") for (int k = 0; k < 2; ++k) \
;         acc[ai][bj][m][n] = __builtin_amdgcn_mfma_f32_16x16x32_bf16(Bt[n][k], At[m][k], acc[ai][bj][m][n], 0, 0, 0); __builtin_amdgcn_s_setprio(0); } while (0)
; #define PG8_WAIT_V(n) asm volatile("s_waitcnt vmcnt(" #n ")" ::: "memory")
; #define PG8_WAIT_L(n) asm volatile("s_waitcnt lgkmcnt(" #n ")" ::: "memory")
; #define PG8_BAR __builtin_amdgcn_s_barrier()
; #define PG8_SCHED __builtin_amdgcn_sched_barrier(0)
; template <class Epi, class Sched, bool ALIGN_EPI = false, bool SP2 = false>
; __device__ __forceinline__ void gemm_phase(PG8_LAS unsigned char* lds, const Gemm g, const Sched& S, const Epi& E) {
;     ...
;             const bool last = (t == nt - 2);
;             const char* a1 = cA + (size_t)(t + 1) * kstep;
;             const char* a2 = last ? nA : cA + (size_t)(t + 2) * kstep; const char* b2 = last ? nB : cB + (size_t)(t + 2) * kstep;
;             const char* a3 = a2 + kstep; const char* b3 = b2 + kstep;
;             if (last && has_next) S.a_ready(nxt);
;             if constexpr (SP2) {
;             PG8_LDB(B0, 0, 0); PG8_LDB(B1, 0, 1); PG8_SCHED; PG8_LDA(At, 0, 0); PG8_STAGE(PG8_SA(1, 1), a1 + hstep, voffA);
;             PG8_WAIT_V(8); PG8_WAIT_L(0); PG8_BAR; PG8_MMA(0, 0, At, B0); PG8_MMA(0, 1, At, B1); PG8_BAR; PG8_SCHED;
;             PG8_LDA(At, 0, 1); PG8_STAGE(PG8_SB(0, 0), b2, voffB); PG8_STAGE(PG8_SB(0, 1), b2 + hstepB, voffB); PG8_STAGE(PG8_SA(0, 0), a2, voffA);
.LBB0_726:
	ds_read_b128 v[130:133], v209
	ds_read_b128 v[134:137], v209 offset:1024
	ds_read_b128 v[138:141], v209 offset:2048
	ds_read_b128 v[142:145], v209 offset:3072
	ds_read_b128 v[146:149], v210
	ds_read_b128 v[150:153], v210 offset:1024
	ds_read_b128 v[154:157], v210 offset:2048
	ds_read_b128 v[158:161], v210 offset:3072
	s_add_u32 s54, s50, 0x4000
	s_addc_u32 s55, s51, 0
	s_cmp_eq_u32 s53, 60
	s_cselect_b32 s68, s29, s54
	s_cselect_b32 s69, s27, s55
	s_cselect_b32 s66, s47, s49
	s_cselect_b32 s67, s37, s52
	s_add_u32 s64, s68, 0x8000
	s_addc_u32 s65, s69, 0
	v_lshl_add_u64 v[206:207], s[50:51], 0, v[198:199]
	s_add_i32 m0, s1, 0xc000
	ds_read_b128 v[162:165], v211
	ds_read_b128 v[166:169], v211 offset:1024
	ds_read_b128 v[170:173], v211 offset:2048
	ds_read_b128 v[174:177], v211 offset:3072
	ds_read_b128 v[178:181], v211 offset:4096
	ds_read_b128 v[182:185], v211 offset:5120
	ds_read_b128 v[224:227], v211 offset:6144
	ds_read_b128 v[228:231], v211 offset:7168
	global_load_lds_dwordx4 v[206:207], off
	v_lshl_add_u64 v[206:207], s[50:51], 0, v[200:201]
	s_add_i32 m0, s1, 0xe000
	s_nop 0
	global_load_lds_dwordx4 v[206:207], off
	s_waitcnt vmcnt(8)
	s_waitcnt lgkmcnt(0)
	s_setprio 1
	s_barrier
	v_mfma_f32_16x16x32_bf16 v[126:129], v[130:133], v[162:165], v[126:129]
	v_mfma_f32_16x16x32_bf16 v[122:125], v[138:141], v[162:165], v[122:125]
	v_mfma_f32_16x16x32_bf16 v[110:113], v[130:133], v[170:173], v[110:113]
	v_mfma_f32_16x16x32_bf16 v[106:109], v[138:141], v[170:173], v[106:109]
	v_mfma_f32_16x16x32_bf16 v[94:97], v[130:133], v[178:181], v[94:97]
	v_mfma_f32_16x16x32_bf16 v[90:93], v[138:141], v[178:181], v[90:93]
	v_mfma_f32_16x16x32_bf16 v[78:81], v[130:133], v[224:227], v[78:81]
	v_mfma_f32_16x16x32_bf16 v[74:77], v[138:141], v[224:227], v[74:77]
	v_mfma_f32_16x16x32_bf16 v[126:129], v[134:137], v[166:169], v[126:129]
	v_mfma_f32_16x16x32_bf16 v[122:125], v[142:145], v[166:169], v[122:125]
	v_mfma_f32_16x16x32_bf16 v[110:113], v[134:137], v[174:177], v[110:113]
	v_mfma_f32_16x16x32_bf16 v[106:109], v[142:145], v[174:177], v[106:109]
	v_mfma_f32_16x16x32_bf16 v[94:97], v[134:137], v[182:185], v[94:97]
	v_mfma_f32_16x16x32_bf16 v[90:93], v[142:145], v[182:185], v[90:93]
	v_mfma_f32_16x16x32_bf16 v[78:81], v[134:137], v[228:231], v[78:81]
	v_mfma_f32_16x16x32_bf16 v[74:77], v[142:145], v[228:231], v[74:77]
	s_setprio 0
	s_setprio 1
	v_mfma_f32_16x16x32_bf16 v[118:121], v[146:149], v[162:165], v[118:121]
	v_mfma_f32_16x16x32_bf16 v[114:117], v[154:157], v[162:165], v[114:117]
	v_mfma_f32_16x16x32_bf16 v[102:105], v[146:149], v[170:173], v[102:105]
	v_mfma_f32_16x16x32_bf16 v[98:101], v[154:157], v[170:173], v[98:101]
	v_mfma_f32_16x16x32_bf16 v[86:89], v[146:149], v[178:181], v[86:89]
	v_mfma_f32_16x16x32_bf16 v[82:85], v[154:157], v[178:181], v[82:85]
	v_mfma_f32_16x16x32_bf16 v[70:73], v[146:149], v[224:227], v[70:73]
	v_mfma_f32_16x16x32_bf16 v[66:69], v[154:157], v[224:227], v[66:69]
	v_mfma_f32_16x16x32_bf16 v[118:121], v[150:153], v[166:169], v[118:121]
	v_mfma_f32_16x16x32_bf16 v[114:117], v[158:161], v[166:169], v[114:117]
	s_barrier
	v_mfma_f32_16x16x32_bf16 v[102:105], v[150:153], v[174:177], v[102:105]
	v_mfma_f32_16x16x32_bf16 v[98:101], v[158:161], v[174:177], v[98:101]
	v_mfma_f32_16x16x32_bf16 v[86:89], v[150:153], v[182:185], v[86:89]
	v_mfma_f32_16x16x32_bf16 v[82:85], v[158:161], v[182:185], v[82:85]
	v_mfma_f32_16x16x32_bf16 v[70:73], v[150:153], v[228:231], v[70:73]
	v_mfma_f32_16x16x32_bf16 v[66:69], v[158:161], v[228:231], v[66:69]
	s_setprio 0
	s_add_i32 s54, s74, s0
	v_lshl_add_u64 v[206:207], s[66:67], 0, v[188:189]
	s_mov_b32 m0, s54
	ds_read_b128 v[162:165], v211 offset:16384
	ds_read_b128 v[166:169], v211 offset:17408
	ds_read_b128 v[170:173], v211 offset:18432
	ds_read_b128 v[174:177], v211 offset:19456
	ds_read_b128 v[178:181], v211 offset:20480
	ds_read_b128 v[182:185], v211 offset:21504
	ds_read_b128 v[224:227], v211 offset:22528
	ds_read_b128 v[228:231], v211 offset:23552
	global_load_lds_dwordx4 v[206:207], off
	s_add_i32 m0, s54, 0x2000
	s_add_u32 s54, s66, 0x1000
	v_lshl_add_u64 v[206:207], s[66:67], 0, v[192:193]
	s_addc_u32 s55, s67, 0
	s_add_i32 s89, s75, s0
	global_load_lds_dwordx4 v[206:207], off
	v_lshl_add_u64 v[206:207], s[54:55], 0, v[188:189]
	s_mov_b32 m0, s89
	s_nop 0
	global_load_lds_dwordx4 v[206:207], off
	v_lshl_add_u64 v[206:207], s[54:55], 0, v[192:193]
	s_add_i32 m0, s89, 0x2000
	s_nop 0
	global_load_lds_dwordx4 v[206:207], off
	v_lshl_add_u64 v[206:207], s[68:69], 0, v[186:187]
	s_mov_b32 m0, s1
	s_nop 0
	global_load_lds_dwordx4 v[206:207], off
	v_lshl_add_u64 v[206:207], s[68:69], 0, v[190:191]
	s_mov_b32 m0, s3
	s_nop 0
	global_load_lds_dwordx4 v[206:207], off
	s_waitcnt vmcnt(8)
	s_waitcnt lgkmcnt(0)
	s_setprio 1
	s_barrier
; #define PG8_STAGE(bufoff, gbase, voff) do { _Pragma("unroll") for (int _i = 0; _i < 2; ++_i) \
;         __builtin_amdgcn_global_load_lds((const unsigned*)((const char*)(gbase) + (voff)[_i]), (PG8_LAS unsigned*)(lds + (bufoff) + ldsw + _i * 8192), 16, 0, 0); } while (0)
; #define PG8_LDA(dst, b, h) do { _Pragma("unroll") for (int m = 0; m < 4; ++m) _Pragma("unroll") for (int k = 0; k < 2; ++k) dst[m][k] = *(const PG8_LAS bf16x8*)(lds + PG8_SA(b, h) + aoff + m * 2048 + k * 1024); } while (0)
; #define PG8_LDB(dst, b, h) do { _Pragma("unroll") for (int n = 0; n < 2; ++n) _Pragma("unroll") for (int k = 0; k < 2; ++k) dst[n][k] = *(const PG8_LAS bf16x8*)(lds + PG8_SB(b, h) + boff + n * 2048 + k * 1024); } while (0)
; #define PG8_MMA(ai, bj, At, Bt) do { __builtin_amdgcn_s_setprio(1); _Pragma("unroll") for (int m = 0; m < 4; ++m) _Pragma("unroll") for (int n = 0; n < 2; ++n) _Pragma("unroll") for (int k = 0; k < 2; ++k) \
;         acc[ai][bj][m][n] = __builtin_amdgcn_mfma_f32_16x16x32_bf16(Bt[n][k], At[m][k], acc[ai][bj][m][n], 0, 0, 0); __builtin_amdgcn_s_setprio(0); } while (0)
; #define PG8_WAIT_V(n) asm volatile("s_waitcnt vmcnt(" #n ")" ::: "memory")
; #define PG8_WAIT_L(n) asm volatile("s_waitcnt lgkmcnt(" #n ")" ::: "memory")
; #define PG8_BAR __builtin_amdgcn_s_barrier()
; #define PG8_SCHED __builtin_amdgcn_sched_barrier(0)
; template <class Epi, class Sched, bool ALIGN_EPI = false, bool SP2 = false>
; __device__ __forceinline__ void gemm_phase(PG8_LAS unsigned char* lds, const Gemm g, const Sched& S, const Epi& E) {
;     ...
;             PG8_LDA(At, 0, 1); PG8_STAGE(PG8_SB(0, 0), b2, voffB); PG8_STAGE(PG8_SB(0, 1), b2 + hstepB, voffB); PG8_STAGE(PG8_SA(0, 0), a2, voffA);
;             PG8_WAIT_V(8); PG8_WAIT_L(0); PG8_BAR; PG8_MMA(1, 0, At, B0); PG8_MMA(1, 1, At, B1); PG8_BAR; PG8_SCHED;
;             PG8_LDB(B0, 1, 0); PG8_LDB(B1, 1, 1); PG8_SCHED; PG8_LDA(At, 1, 0); PG8_STAGE(PG8_SA(0, 1), a2 + hstep, voffA);
;             PG8_WAIT_V(8); PG8_WAIT_L(0); PG8_BAR; PG8_MMA(0, 0, At, B0); PG8_MMA(0, 1, At, B1); PG8_BAR; PG8_SCHED;
	v_mfma_f32_16x16x32_bf16 v[62:65], v[130:133], v[162:165], v[62:65]
	v_mfma_f32_16x16x32_bf16 v[58:61], v[138:141], v[162:165], v[58:61]
	v_mfma_f32_16x16x32_bf16 v[46:49], v[130:133], v[170:173], v[46:49]
	v_mfma_f32_16x16x32_bf16 v[42:45], v[138:141], v[170:173], v[42:45]
	v_mfma_f32_16x16x32_bf16 v[30:33], v[130:133], v[178:181], v[30:33]
	v_mfma_f32_16x16x32_bf16 v[26:29], v[138:141], v[178:181], v[26:29]
	v_mfma_f32_16x16x32_bf16 v[14:17], v[130:133], v[224:227], v[14:17]
	v_mfma_f32_16x16x32_bf16 v[10:13], v[138:141], v[224:227], v[10:13]
	v_mfma_f32_16x16x32_bf16 v[62:65], v[134:137], v[166:169], v[62:65]
	v_mfma_f32_16x16x32_bf16 v[58:61], v[142:145], v[166:169], v[58:61]
	v_mfma_f32_16x16x32_bf16 v[46:49], v[134:137], v[174:177], v[46:49]
	v_mfma_f32_16x16x32_bf16 v[42:45], v[142:145], v[174:177], v[42:45]
	v_mfma_f32_16x16x32_bf16 v[30:33], v[134:137], v[182:185], v[30:33]
	v_mfma_f32_16x16x32_bf16 v[26:29], v[142:145], v[182:185], v[26:29]
	v_mfma_f32_16x16x32_bf16 v[14:17], v[134:137], v[228:231], v[14:17]
	v_mfma_f32_16x16x32_bf16 v[10:13], v[142:145], v[228:231], v[10:13]
	s_setprio 0
	s_setprio 1
	v_mfma_f32_16x16x32_bf16 v[54:57], v[146:149], v[162:165], v[54:57]
	v_mfma_f32_16x16x32_bf16 v[50:53], v[154:157], v[162:165], v[50:53]
	v_mfma_f32_16x16x32_bf16 v[38:41], v[146:149], v[170:173], v[38:41]
	v_mfma_f32_16x16x32_bf16 v[34:37], v[154:157], v[170:173], v[34:37]
	v_mfma_f32_16x16x32_bf16 v[22:25], v[146:149], v[178:181], v[22:25]
	v_mfma_f32_16x16x32_bf16 v[18:21], v[154:157], v[178:181], v[18:21]
	v_mfma_f32_16x16x32_bf16 v[6:9], v[146:149], v[224:227], v[6:9]
	v_mfma_f32_16x16x32_bf16 v[2:5], v[154:157], v[224:227], v[2:5]
	v_mfma_f32_16x16x32_bf16 v[54:57], v[150:153], v[166:169], v[54:57]
	v_mfma_f32_16x16x32_bf16 v[50:53], v[158:161], v[166:169], v[50:53]
	s_barrier
	v_mfma_f32_16x16x32_bf16 v[38:41], v[150:153], v[174:177], v[38:41]
	v_mfma_f32_16x16x32_bf16 v[34:37], v[158:161], v[174:177], v[34:37]
	v_mfma_f32_16x16x32_bf16 v[22:25], v[150:153], v[182:185], v[22:25]
	v_mfma_f32_16x16x32_bf16 v[18:21], v[158:161], v[182:185], v[18:21]
	v_mfma_f32_16x16x32_bf16 v[6:9], v[150:153], v[228:231], v[6:9]
	v_mfma_f32_16x16x32_bf16 v[2:5], v[158:161], v[228:231], v[2:5]
	s_setprio 0
	s_add_i32 s89, 0, 0x18000
	s_add_i32 s90, 0, 0x1c000
	v_add_u32_e32 v142, s89, v214
	v_add_u32_e32 v158, s90, v214
	ds_read_b128 v[130:133], v142
	ds_read_b128 v[134:137], v142 offset:1024
	ds_read_b128 v[138:141], v142 offset:2048
	ds_read_b128 v[142:145], v142 offset:3072
	ds_read_b128 v[146:149], v158
	ds_read_b128 v[150:153], v158 offset:1024
	ds_read_b128 v[154:157], v158 offset:2048
	ds_read_b128 v[158:161], v158 offset:3072
	s_add_u32 s54, s68, 0x4000
	s_addc_u32 s55, s69, 0
	s_mov_b32 m0, s56
	v_lshl_add_u64 v[206:207], s[54:55], 0, v[186:187]
	ds_read_b128 v[162:165], v211 offset:32768
	ds_read_b128 v[166:169], v211 offset:33792
	ds_read_b128 v[170:173], v211 offset:34816
	ds_read_b128 v[174:177], v211 offset:35840
	ds_read_b128 v[178:181], v211 offset:36864
	ds_read_b128 v[182:185], v211 offset:37888
	ds_read_b128 v[224:227], v211 offset:38912
	ds_read_b128 v[228:231], v211 offset:39936
	global_load_lds_dwordx4 v[206:207], off
	v_lshl_add_u64 v[206:207], s[54:55], 0, v[190:191]
	s_mov_b32 m0, s57
	s_nop 0
	global_load_lds_dwordx4 v[206:207], off
	s_waitcnt vmcnt(8)
	s_waitcnt lgkmcnt(0)
	s_setprio 1
	s_barrier
	v_mfma_f32_16x16x32_bf16 v[126:129], v[130:133], v[162:165], v[126:129]
	v_mfma_f32_16x16x32_bf16 v[122:125], v[138:141], v[162:165], v[122:125]
	v_mfma_f32_16x16x32_bf16 v[110:113], v[130:133], v[170:173], v[110:113]
	v_mfma_f32_16x16x32_bf16 v[106:109], v[138:141], v[170:173], v[106:109]
	v_mfma_f32_16x16x32_bf16 v[94:97], v[130:133], v[178:181], v[94:97]
	v_mfma_f32_16x16x32_bf16 v[90:93], v[138:141], v[178:181], v[90:93]
	v_mfma_f32_16x16x32_bf16 v[78:81], v[130:133], v[224:227], v[78:81]
	v_mfma_f32_16x16x32_bf16 v[74:77], v[138:141], v[224:227], v[74:77]
	v_mfma_f32_16x16x32_bf16 v[126:129], v[134:137], v[166:169], v[126:129]
	v_mfma_f32_16x16x32_bf16 v[122:125], v[142:145], v[166:169], v[122:125]
	v_mfma_f32_16x16x32_bf16 v[110:113], v[134:137], v[174:177], v[110:113]
	v_mfma_f32_16x16x32_bf16 v[106:109], v[142:145], v[174:177], v[106:109]
	v_mfma_f32_16x16x32_bf16 v[94:97], v[134:137], v[182:185], v[94:97]
	v_mfma_f32_16x16x32_bf16 v[90:93], v[142:145], v[182:185], v[90:93]
	v_mfma_f32_16x16x32_bf16 v[78:81], v[134:137], v[228:231], v[78:81]
	v_mfma_f32_16x16x32_bf16 v[74:77], v[142:145], v[228:231], v[74:77]
	s_setprio 0
	s_setprio 1
	v_mfma_f32_16x16x32_bf16 v[118:121], v[146:149], v[162:165], v[118:121]
	v_mfma_f32_16x16x32_bf16 v[114:117], v[154:157], v[162:165], v[114:117]
	v_mfma_f32_16x16x32_bf16 v[102:105], v[146:149], v[170:173], v[102:105]
	v_mfma_f32_16x16x32_bf16 v[98:101], v[154:157], v[170:173], v[98:101]
	v_mfma_f32_16x16x32_bf16 v[86:89], v[146:149], v[178:181], v[86:89]
	v_mfma_f32_16x16x32_bf16 v[82:85], v[154:157], v[178:181], v[82:85]
	v_mfma_f32_16x16x32_bf16 v[70:73], v[146:149], v[224:227], v[70:73]
	v_mfma_f32_16x16x32_bf16 v[66:69], v[154:157], v[224:227], v[66:69]
	v_mfma_f32_16x16x32_bf16 v[118:121], v[150:153], v[166:169], v[118:121]
	v_mfma_f32_16x16x32_bf16 v[114:117], v[158:161], v[166:169], v[114:117]
	s_barrier
; #define PG8_STAGE(bufoff, gbase, voff) do { _Pragma("unroll") for (int _i = 0; _i < 2; ++_i) \
;         __builtin_amdgcn_global_load_lds((const unsigned*)((const char*)(gbase) + (voff)[_i]), (PG8_LAS unsigned*)(lds + (bufoff) + ldsw + _i * 8192), 16, 0, 0); } while (0)
; #define PG8_LDA(dst, b, h) do { _Pragma("unroll") for (int m = 0; m < 4; ++m) _Pragma("unroll") for (int k = 0; k < 2; ++k) dst[m][k] = *(const PG8_LAS bf16x8*)(lds + PG8_SA(b, h) + aoff + m * 2048 + k * 1024); } while (0)
; #define PG8_MMA(ai, bj, At, Bt) do { __builtin_amdgcn_s_setprio(1); _Pragma("unroll") for (int m = 0; m < 4; ++m) _Pragma("unroll") for (int n = 0; n < 2; ++n) _Pragma("unroll") for (int k = 0; k < 2; ++k) \
;         acc[ai][bj][m][n] = __builtin_amdgcn_mfma_f32_16x16x32_bf16(Bt[n][k], At[m][k], acc[ai][bj][m][n], 0, 0, 0); __builtin_amdgcn_s_setprio(0); } while (0)
; #define PG8_WAIT_V(n) asm volatile("s_waitcnt vmcnt(" #n ")" ::: "memory")
; #define PG8_WAIT_L(n) asm volatile("s_waitcnt lgkmcnt(" #n ")" ::: "memory")
; #define PG8_BAR __builtin_amdgcn_s_barrier()
; #define PG8_SCHED __builtin_amdgcn_sched_barrier(0)
; template <class Epi, class Sched, bool ALIGN_EPI = false, bool SP2 = false>
; __device__ __forceinline__ void gemm_phase(PG8_LAS unsigned char* lds, const Gemm g, const Sched& S, const Epi& E) {
;     ...
;             PG8_WAIT_V(8); PG8_WAIT_L(0); PG8_BAR; PG8_MMA(0, 0, At, B0); PG8_MMA(0, 1, At, B1); PG8_BAR; PG8_SCHED;
;             PG8_LDA(At, 1, 1); PG8_STAGE(PG8_SB(1, 0), b3, voffB); PG8_STAGE(PG8_SB(1, 1), b3 + hstepB, voffB); PG8_STAGE(PG8_SA(1, 0), a3, voffA);
;             PG8_WAIT_V(8); PG8_WAIT_L(0); PG8_BAR; PG8_MMA(1, 0, At, B0); PG8_MMA(1, 1, At, B1); PG8_BAR; PG8_SCHED;
;     ...
;         if constexpr (ALIGN_EPI) { if (wr == 0) PG8_BAR; }
	v_mfma_f32_16x16x32_bf16 v[102:105], v[150:153], v[174:177], v[102:105]
	v_mfma_f32_16x16x32_bf16 v[98:101], v[158:161], v[174:177], v[98:101]
	v_mfma_f32_16x16x32_bf16 v[86:89], v[150:153], v[182:185], v[86:89]
	v_mfma_f32_16x16x32_bf16 v[82:85], v[158:161], v[182:185], v[82:85]
	v_mfma_f32_16x16x32_bf16 v[70:73], v[150:153], v[228:231], v[70:73]
	v_mfma_f32_16x16x32_bf16 v[66:69], v[158:161], v[228:231], v[66:69]
	s_setprio 0
	s_add_u32 s54, s66, 0x8000
	s_addc_u32 s55, s67, 0
	s_add_i32 s68, s89, s0
	v_lshl_add_u64 v[206:207], s[54:55], 0, v[188:189]
	s_mov_b32 m0, s68
	ds_read_b128 v[162:165], v211 offset:49152
	ds_read_b128 v[166:169], v211 offset:50176
	ds_read_b128 v[170:173], v211 offset:51200
	ds_read_b128 v[174:177], v211 offset:52224
	ds_read_b128 v[178:181], v211 offset:53248
	ds_read_b128 v[182:185], v211 offset:54272
	ds_read_b128 v[224:227], v211 offset:55296
	ds_read_b128 v[228:231], v211 offset:56320
	global_load_lds_dwordx4 v[206:207], off
	s_add_i32 m0, s68, 0x2000
	v_lshl_add_u64 v[206:207], s[54:55], 0, v[192:193]
	s_add_u32 s54, s66, 0x9000
	s_addc_u32 s55, s67, 0
	s_add_i32 s66, s90, s0
	global_load_lds_dwordx4 v[206:207], off
	v_lshl_add_u64 v[206:207], s[54:55], 0, v[188:189]
	s_mov_b32 m0, s66
	s_nop 0
	global_load_lds_dwordx4 v[206:207], off
	v_lshl_add_u64 v[206:207], s[54:55], 0, v[192:193]
	s_add_i32 m0, s66, 0x2000
	s_nop 0
	global_load_lds_dwordx4 v[206:207], off
	v_lshl_add_u64 v[206:207], s[64:65], 0, v[186:187]
	s_mov_b32 m0, s71
	s_nop 0
	global_load_lds_dwordx4 v[206:207], off
	v_lshl_add_u64 v[206:207], s[64:65], 0, v[190:191]
	s_mov_b32 m0, s72
	s_nop 0
	global_load_lds_dwordx4 v[206:207], off
	s_waitcnt vmcnt(8)
	s_waitcnt lgkmcnt(0)
	s_setprio 1
	s_barrier
	v_mfma_f32_16x16x32_bf16 v[62:65], v[130:133], v[162:165], v[62:65]
	v_mfma_f32_16x16x32_bf16 v[58:61], v[138:141], v[162:165], v[58:61]
	v_mfma_f32_16x16x32_bf16 v[46:49], v[130:133], v[170:173], v[46:49]
	v_mfma_f32_16x16x32_bf16 v[42:45], v[138:141], v[170:173], v[42:45]
	v_mfma_f32_16x16x32_bf16 v[30:33], v[130:133], v[178:181], v[30:33]
	v_mfma_f32_16x16x32_bf16 v[26:29], v[138:141], v[178:181], v[26:29]
	v_mfma_f32_16x16x32_bf16 v[14:17], v[130:133], v[224:227], v[14:17]
	v_mfma_f32_16x16x32_bf16 v[10:13], v[138:141], v[224:227], v[10:13]
	v_mfma_f32_16x16x32_bf16 v[62:65], v[134:137], v[166:169], v[62:65]
	v_mfma_f32_16x16x32_bf16 v[58:61], v[142:145], v[166:169], v[58:61]
	v_mfma_f32_16x16x32_bf16 v[46:49], v[134:137], v[174:177], v[46:49]
	v_mfma_f32_16x16x32_bf16 v[42:45], v[142:145], v[174:177], v[42:45]
	v_mfma_f32_16x16x32_bf16 v[30:33], v[134:137], v[182:185], v[30:33]
	v_mfma_f32_16x16x32_bf16 v[26:29], v[142:145], v[182:185], v[26:29]
	v_mfma_f32_16x16x32_bf16 v[14:17], v[134:137], v[228:231], v[14:17]
	v_mfma_f32_16x16x32_bf16 v[10:13], v[142:145], v[228:231], v[10:13]
	s_setprio 0
	s_setprio 1
	v_mfma_f32_16x16x32_bf16 v[54:57], v[146:149], v[162:165], v[54:57]
	v_mfma_f32_16x16x32_bf16 v[50:53], v[154:157], v[162:165], v[50:53]
	v_mfma_f32_16x16x32_bf16 v[38:41], v[146:149], v[170:173], v[38:41]
	v_mfma_f32_16x16x32_bf16 v[34:37], v[154:157], v[170:173], v[34:37]
	v_mfma_f32_16x16x32_bf16 v[22:25], v[146:149], v[178:181], v[22:25]
	v_mfma_f32_16x16x32_bf16 v[18:21], v[154:157], v[178:181], v[18:21]
	v_mfma_f32_16x16x32_bf16 v[6:9], v[146:149], v[224:227], v[6:9]
	v_mfma_f32_16x16x32_bf16 v[2:5], v[154:157], v[224:227], v[2:5]
	v_mfma_f32_16x16x32_bf16 v[54:57], v[150:153], v[166:169], v[54:57]
	v_mfma_f32_16x16x32_bf16 v[50:53], v[158:161], v[166:169], v[50:53]
	s_barrier
	v_mfma_f32_16x16x32_bf16 v[38:41], v[150:153], v[174:177], v[38:41]
	v_mfma_f32_16x16x32_bf16 v[34:37], v[158:161], v[174:177], v[34:37]
	v_mfma_f32_16x16x32_bf16 v[22:25], v[150:153], v[182:185], v[22:25]
	v_mfma_f32_16x16x32_bf16 v[18:21], v[158:161], v[182:185], v[18:21]
	v_mfma_f32_16x16x32_bf16 v[6:9], v[150:153], v[228:231], v[6:9]
	v_mfma_f32_16x16x32_bf16 v[2:5], v[158:161], v[228:231], v[2:5]
	s_setprio 0
	s_add_i32 s53, s53, 2
	s_add_u32 s50, s50, 0x10000
	s_addc_u32 s51, s51, 0
	s_add_u32 s49, s49, 0x10000
	s_addc_u32 s52, s52, 0
	s_cmp_gt_u32 s53, 61
	s_cbranch_scc0 .LBB0_726
	s_and_b64 vcc, exec, s[20:21]
	s_cbranch_vccz .LBB0_729
	s_barrier
